# attn-C: V tile LDS row order changed (no bit2/3 key swap) so P fragments feed PV MFMA without the 8 permlane32 half-swaps per tile
# speedup vs baseline: 1.0214x; 1.0062x over previous
; __device__ __forceinline__ int tid_() { int t = (int)threadIdx.x; asm volatile("" : "+v"(t)); return t; }
; __device__ __forceinline__ int v_rd_base(int lane) { return ((lane & 3) << 3) | (((lane >> 2) & 3) << 6) | (((lane >> 4) & 1) << 5) | (((lane >> 5) & 1) << 8); }
; #define SLOAD(i, k0) do { sv0[i] = *(const bf16x8*)(&Vh[(long)((k0) + sr) * LDK + sc]); sv1[i] = *(const bf16x8*)(&Vh[(long)((k0) + 32 + sr) * LDK + sc]); \
;     sk0[i] = *(const bf16x8*)(&Kh[(long)((k0) + sr) * LDK + sc]); sk1[i] = *(const bf16x8*)(&Kh[(long)((k0) + 32 + sr) * LDK + sc]); } while (0)
; #define SWRITE(off, i) do { *(bf16x8*)((char*)V_lds + (off) + vst0) = sv0[i];          \
;     *(bf16x8*)((char*)V_lds + (off) + vst1) = sv1[i]; int kc = sc * 2;               \
;     *(bf16x8*)((char*)K_lds + (off) + KSWZ(sr, kc)) = sk0[i];                       \
;     *(bf16x8*)((char*)K_lds + (off) + KSWZ(32 + sr, kc)) = sk1[i]; } while (0)
; __device__ __forceinline__ int v_st(int k, int c) { const int kk = (k & ~0xC) | ((k & 4) << 1) | ((k & 8) >> 1); return ((kk >> 3) * 4 + (c >> 5)) * 512 + ((kk & 7) * 32 + (c & 31)) * 2; }
; __device__ __forceinline__ void attn_dense_body(const bf16_t* __restrict__ Qb, const bf16_t* __restrict__ Kh, const bf16_t* __restrict__ Vh,
;                                                 bf16_t* __restrict__ Ob, int seq, char* lds, int dry) {
;     const int tid = tid_(), wid = tid >> 6, lane = tid & 63, r32 = lane & 31, hi = lane >> 5;
;     bf16_t* V_lds = (bf16_t*)lds; bf16_t* K_lds = (bf16_t*)(lds + 3 * SHM_V);
;     float* ws = (float*)(lds + 3 * SHM_V + 3 * SHM_K) + wid * 64; float* li_l = ws; float* al_l = ws + 32;
;     float m_reg = -1e30f, l_reg = 0; f32x16 o[4] = {}; bf16x8 qr[8];
;     const bf16_t* Qw = Qb + (long)(wid * QBLK + r32) * LDQ + hi * 8;
; #pragma unroll
;     for (int d0 = 0; d0 < 8; ++d0) qr[d0] = *reinterpret_cast<const bf16x8*>(Qw + d0 * 16);
;     const int sr = tid >> 4, sc = (tid & 15) * 8, vst0 = v_st(sr, sc), vst1 = v_st(32 + sr, sc);
;     const int vb0 = (int)(uintptr_t)V_lds + v_rd_base(lane);
;     bf16x8 sv0[2], sv1[2], sk0[2], sk1[2];
;     ...
;     f32x16 pA0, pA1, pB0, pB1; float mnA, mnB, alA, alB; bf16x8 pa0, pa1, pa2, pa3; const int NT = seq / KVBLK;
;     SLOAD(0, 0); asm volatile("s_waitcnt vmcnt(0)" ::: "memory"); SWRITE(0, 0); __syncthreads();
.LBB0_268:
	s_lshl_b32 s4, s29, 5
	s_cmpk_lt_i32 s29, 0x400
	s_movk_i32 s7, 0xc000
	s_cselect_b32 s5, 6, 4
	s_cselect_b32 s6, 63, 15
	s_cselect_b32 s7, s7, 0x7ffff000
	s_movk_i32 s37, 0x4000
	s_cselect_b32 s8, s37, 0xffff8000
	s_cselect_b32 s36, 0x100, 64
	s_lshr_b32 s12, s29, s5
	s_and_b32 s5, s6, s29
	s_and_b32 s4, s7, s4
	s_add_i32 s8, s4, s8
	s_lshl_b32 s4, s5, 8
	s_add_i32 s4, s8, s4
	s_and_b32 s6, s12, 7
	s_ashr_i32 s5, s4, 31
	s_mul_i32 s9, s4, 0xc00
	s_mul_hi_i32 s7, s4, 0xc00
	s_add_u32 s9, s30, s9
	s_addc_u32 s7, s31, s7
	s_lshl_b32 s35, s6, 7
	s_lshl_b32 s6, s6, 8
	s_add_u32 s10, s9, s6
	s_addc_u32 s11, s7, 0
	s_ashr_i32 s9, s8, 31
	s_mul_i32 s7, s8, 0xc00
	s_mul_hi_i32 s6, s8, 0xc00
	s_add_u32 s7, s30, s7
	s_addc_u32 s13, s31, s6
	s_lshl_b32 s6, s12, 6
	s_and_b32 s39, s6, 0x100
	v_mov_b32_e32 v70, v182
	s_add_u32 s6, s7, s39
	s_addc_u32 s7, s13, 0
	v_ashrrev_i32_e32 v48, 4, v70
	v_lshlrev_b32_e32 v18, 3, v70
	v_and_b32_e32 v71, 0x78, v18
	s_waitcnt vmcnt(0)
	v_mad_i64_i32 v[0:1], s[12:13], v48, s71, 0
	v_add_u32_e32 v19, 32, v48
	v_or_b32_e32 v0, v0, v71
	v_lshl_add_u64 v[8:9], v[0:1], 1, s[6:7]
	v_mad_i64_i32 v[4:5], s[12:13], v19, s71, 0
	global_load_dwordx4 v[0:3], v[8:9], off offset:2560
	v_or_b32_e32 v4, v4, v71
	v_lshl_add_u64 v[12:13], v[4:5], 1, s[6:7]
	global_load_dwordx4 v[4:7], v[12:13], off offset:2560
	s_nop 0
	global_load_dwordx4 v[8:11], v[8:9], off offset:2048
	s_nop 0
	global_load_dwordx4 v[12:15], v[12:13], off offset:2048
	v_ashrrev_i32_e32 v49, 1, v70
	s_movk_i32 s12, 0xffe0
	v_bfe_u32 v207, v70, 5, 1
	v_bfi_b32 v20, s12, v49, v70
	v_mov_b64_e32 v[16:17], s[10:11]
	v_mad_i64_i32 v[16:17], s[10:11], v20, s70, v[16:17]
	v_lshlrev_b32_e32 v96, 4, v207
	v_lshl_add_u64 v[16:17], v[16:17], 0, v[96:97]
	global_load_dwordx4 v[126:129], v[16:17], off
	global_load_dwordx4 v[122:125], v[16:17], off offset:32
	global_load_dwordx4 v[118:121], v[16:17], off offset:64
	global_load_dwordx4 v[114:117], v[16:17], off offset:96
	global_load_dwordx4 v[110:113], v[16:17], off offset:128
	global_load_dwordx4 v[106:109], v[16:17], off offset:160
	global_load_dwordx4 v[102:105], v[16:17], off offset:192
	global_load_dwordx4 v[98:101], v[16:17], off offset:224
	v_and_b32_e32 v21, 0xfffff0, v48
	v_lshlrev_b32_e32 v22, 1, v48
	v_lshrrev_b32_e32 v23, 1, v48
	v_and_b32_e32 v24, 3, v48
	v_and_or_b32 v21, v22, 8, v21
	v_and_or_b32 v22, v23, 4, v24
	v_and_b32_e32 v24, 0xfffff0, v19
	v_lshlrev_b32_e32 v26, 1, v19
	v_bfe_u32 v18, v18, 5, 2
	v_lshrrev_b32_e32 v21, 1, v21
	v_and_or_b32 v24, v26, 8, v24
	v_lshlrev_b32_e32 v23, 1, v71
	v_or_b32_e32 v21, v21, v18
	v_lshrrev_b32_e32 v24, 1, v24
	v_lshlrev_b32_e32 v22, 6, v22
	v_and_b32_e32 v27, 48, v23
	v_lshlrev_b32_e32 v21, 9, v21
	v_or_b32_e32 v18, v24, v18
	v_and_b32_e32 v20, 0x70, v70
	v_lshlrev_b32_e32 v25, 8, v48
	v_or3_b32 v216, v21, v22, v27
	v_lshlrev_b32_e32 v18, 9, v18
	v_bitop3_b32 v214, v23, v25, v20 bitop3:0xde
	v_and_b32_e32 v252, 0x80, v182
	v_lshlrev_b32_e32 v253, 4, v182
	v_and_b32_e32 v253, 0x80, v253
	v_xor_b32_e32 v214, v214, v252
	v_or3_b32 v217, v18, v22, v27
	v_bfe_u32 v250, v182, 7, 2
	v_lshlrev_b32_e32 v250, 11, v250
	v_bfe_u32 v251, v182, 4, 3
	v_lshl_or_b32 v250, v251, 6, v250
	v_bfe_u32 v251, v182, 2, 2
	v_lshl_or_b32 v250, v251, 9, v250
	v_and_b32_e32 v251, 3, v182
	v_lshl_or_b32 v216, v251, 4, v250
	v_add_u32_e32 v217, 0x2000, v216
	v_add_u32_e32 v72, 0, v216
	v_and_b32_e32 v208, 31, v70
	v_lshlrev_b32_e32 v50, 4, v70
	v_add_u32_e32 v73, 0, v217
	s_waitcnt vmcnt(0)
	s_add_i32 s10, 0, 0x18000
	v_and_b32_e32 v74, 63, v70
	s_cmp_lg_u32 0, -1
	s_mov_b32 s12, 0
	s_mov_b32 s13, s12
	v_and_b32_e32 v178, 0xffffffe0, v49
	s_waitcnt vmcnt(11)
	ds_write_b128 v72, v[0:3]
	s_waitcnt vmcnt(10)
	ds_write_b128 v73, v[4:7]
	v_add_u32_e32 v0, 0, v214
	s_waitcnt vmcnt(9)
	ds_write_b128 v0, v[8:11] offset:49152
	v_lshlrev_b32_e32 v0, 8, v19
	v_lshlrev_b32_e32 v8, 8, v208
	v_and_b32_e32 v9, 0x70, v50
	v_bitop3_b32 v219, v23, v0, v20 bitop3:0xde
	v_xor_b32_e32 v219, v219, v252
	v_bitop3_b32 v220, v96, v8, v9 bitop3:0xde
	v_xor_b32_e32 v220, v220, v253
	v_add_u32_e32 v0, 0, v219
	v_add_u32_e32 v4, 0, v220
	s_waitcnt vmcnt(8)
	ds_write_b128 v0, v[12:15] offset:49152
	s_waitcnt lgkmcnt(0)
	s_barrier
	ds_read_b128 v[0:3], v4 offset:49152
	ds_read_b128 v[4:7], v4 offset:57344
	s_waitcnt vmcnt(7) lgkmcnt(1)
	v_mfma_f32_32x32x16_bf16 v[16:31], v[0:3], v[126:129], 0
	v_or_b32_e32 v0, 32, v96
	v_bitop3_b32 v222, v0, v8, v9 bitop3:0xde
	v_xor_b32_e32 v222, v222, v253
	v_ashrrev_i32_e32 v49, 31, v48
	s_mov_b32 s14, s12
	s_mov_b32 s15, s12
	s_mov_b32 s16, s12
	s_mov_b32 s17, s12
	s_waitcnt lgkmcnt(0)
	v_mfma_f32_32x32x16_bf16 v[32:47], v[4:7], v[126:129], 0
	v_add_u32_e32 v4, 0, v222
	ds_read_b128 v[0:3], v4 offset:49152
	ds_read_b128 v[4:7], v4 offset:57344
	s_mov_b32 s18, s12
	s_mov_b32 s19, s12
	s_mov_b32 s20, s12
	s_mov_b32 s21, s12
	s_mov_b32 s22, s12
	s_waitcnt vmcnt(6) lgkmcnt(1)
	v_mfma_f32_32x32x16_bf16 v[16:31], v[0:3], v[122:125], v[16:31]
	v_or_b32_e32 v0, 64, v96
	v_bitop3_b32 v221, v0, v8, v9 bitop3:0xde
	v_xor_b32_e32 v221, v221, v253
	s_mov_b32 s23, s12
	s_mov_b32 s24, s12
	s_mov_b32 s25, s12
	s_mov_b32 s26, s12
	s_mov_b32 s27, s12
	s_waitcnt lgkmcnt(0)
	v_mfma_f32_32x32x16_bf16 v[32:47], v[4:7], v[122:125], v[32:47]
	v_add_u32_e32 v4, 0, v221
	ds_read_b128 v[0:3], v4 offset:49152
	ds_read_b128 v[4:7], v4 offset:57344
	s_mov_b32 s38, 2
	v_mov_b32_e32 v210, 0
	s_waitcnt vmcnt(5) lgkmcnt(1)
	v_mfma_f32_32x32x16_bf16 v[16:31], v[0:3], v[118:121], v[16:31]
	v_or_b32_e32 v0, 0x60, v96
	v_bitop3_b32 v218, v0, v8, v9 bitop3:0xde
	v_xor_b32_e32 v218, v218, v253
	s_waitcnt lgkmcnt(0)
; #define SLOAD(i, k0) do { sv0[i] = *(const bf16x8*)(&Vh[(long)((k0) + sr) * LDK + sc]); sv1[i] = *(const bf16x8*)(&Vh[(long)((k0) + 32 + sr) * LDK + sc]); \
;     sk0[i] = *(const bf16x8*)(&Kh[(long)((k0) + sr) * LDK + sc]); sk1[i] = *(const bf16x8*)(&Kh[(long)((k0) + 32 + sr) * LDK + sc]); } while (0)
; #define SWRITE(off, i) do { *(bf16x8*)((char*)V_lds + (off) + vst0) = sv0[i];          \
;     *(bf16x8*)((char*)V_lds + (off) + vst1) = sv1[i]; int kc = sc * 2;               \
;     *(bf16x8*)((char*)K_lds + (off) + KSWZ(sr, kc)) = sk0[i];                       \
;     *(bf16x8*)((char*)K_lds + (off) + KSWZ(32 + sr, kc)) = sk1[i]; } while (0)
; #define SWAIT() asm volatile("s_waitcnt vmcnt(4)" ::: "memory")
; __device__ __forceinline__ void attn_dense_body(const bf16_t* __restrict__ Qb, const bf16_t* __restrict__ Kh, const bf16_t* __restrict__ Vh,
;                                                 bf16_t* __restrict__ Ob, int seq, char* lds, int dry) {
;     ...
;     SLOAD(0, 0); asm volatile("s_waitcnt vmcnt(0)" ::: "memory"); SWRITE(0, 0); __syncthreads();
;     qkt(pA0, pA1, K_lds, qr, r32, hi); partialSM(pA0, pA1, m_reg, mnA, alA);
;     SLOAD(1, KVBLK); if (2 < NT) SLOAD(0, 2 * KVBLK);
;     SWAIT(); SWRITE((int)SHM_K, 1); __syncthreads();
	v_mfma_f32_32x32x16_bf16 v[32:47], v[4:7], v[118:121], v[32:47]
	v_add_u32_e32 v4, 0, v218
	ds_read_b128 v[0:3], v4 offset:49152
	ds_read_b128 v[4:7], v4 offset:57344
	s_waitcnt vmcnt(4) lgkmcnt(1)
	v_mfma_f32_32x32x16_bf16 v[16:31], v[0:3], v[114:117], v[16:31]
	v_or_b32_e32 v0, 0x80, v96
	v_bitop3_b32 v215, v0, v8, v9 bitop3:0xde
	v_xor_b32_e32 v215, v215, v253
	s_waitcnt lgkmcnt(0)
	v_mfma_f32_32x32x16_bf16 v[32:47], v[4:7], v[114:117], v[32:47]
	v_add_u32_e32 v4, 0, v215
	ds_read_b128 v[0:3], v4 offset:49152
	ds_read_b128 v[4:7], v4 offset:57344
	s_waitcnt vmcnt(3) lgkmcnt(1)
	v_mfma_f32_32x32x16_bf16 v[16:31], v[0:3], v[110:113], v[16:31]
	v_or_b32_e32 v0, 0xa0, v96
	v_bitop3_b32 v213, v0, v8, v9 bitop3:0xde
	v_xor_b32_e32 v213, v213, v253
	s_waitcnt lgkmcnt(0)
	v_mfma_f32_32x32x16_bf16 v[32:47], v[4:7], v[110:113], v[32:47]
	v_add_u32_e32 v4, 0, v213
	ds_read_b128 v[0:3], v4 offset:49152
	v_and_b32_e32 v5, 0x3fffffc0, v70
	v_lshl_add_u32 v179, v5, 2, s10
	ds_read_b128 v[4:7], v4 offset:57344
	v_lshl_add_u32 v209, v208, 2, v179
	s_waitcnt vmcnt(2) lgkmcnt(1)
	v_mfma_f32_32x32x16_bf16 v[16:31], v[0:3], v[106:109], v[16:31]
	v_lshlrev_b32_e32 v0, 3, v74
	v_and_b32_e32 v1, 0xc0, v50
	v_and_or_b32 v10, v0, 24, v1
	v_lshlrev_b32_e32 v1, 1, v70
	v_and_b32_e32 v12, 0x100, v0
	v_add_u32_e32 v0, 64, v48
	v_and_b32_e32 v11, 32, v1
	s_waitcnt lgkmcnt(0)
	v_mfma_f32_32x32x16_bf16 v[32:47], v[4:7], v[106:109], v[32:47]
	v_or_b32_e32 v6, 0xc0, v96
	v_mad_i64_i32 v[0:1], s[10:11], v0, s71, 0
	v_add_u32_e32 v2, 0x60, v48
	v_or_b32_e32 v0, v0, v71
	v_mad_i64_i32 v[2:3], s[10:11], v2, s71, 0
	v_bitop3_b32 v223, v6, v8, v9 bitop3:0xde
	v_xor_b32_e32 v223, v223, v253
	v_lshl_add_u64 v[0:1], v[0:1], 1, s[6:7]
	v_or_b32_e32 v2, v2, v71
	v_add_u32_e32 v6, 0, v223
	global_load_dwordx4 v[50:53], v[0:1], off offset:2560
	global_load_dwordx4 v[58:61], v[0:1], off offset:2048
	v_lshl_add_u64 v[4:5], v[2:3], 1, s[6:7]
	ds_read_b128 v[0:3], v6 offset:49152
	s_waitcnt vmcnt(3) lgkmcnt(0)
	v_mfma_f32_32x32x16_bf16 v[16:31], v[0:3], v[102:105], v[16:31]
	v_or_b32_e32 v0, 0xe0, v96
	v_bitop3_b32 v224, v0, v8, v9 bitop3:0xde
	v_xor_b32_e32 v224, v224, v253
	global_load_dwordx4 v[54:57], v[4:5], off offset:2560
	global_load_dwordx4 v[62:65], v[4:5], off offset:2048
	v_or3_b32 v4, v10, v11, v12
	s_cselect_b32 s10, 0, 0
	v_add_u32_e32 v8, 0, v224
	v_add_u32_e32 v212, s10, v4
	ds_read_b128 v[4:7], v6 offset:57344
	ds_read_b128 v[0:3], v8 offset:49152
	ds_read_b128 v[66:69], v8 offset:57344
	s_waitcnt lgkmcnt(2)
	v_mfma_f32_32x32x16_bf16 v[32:47], v[4:7], v[102:105], v[32:47]
	s_waitcnt vmcnt(4) lgkmcnt(1)
	v_mfma_f32_32x32x16_bf16 v[16:31], v[0:3], v[98:101], v[16:31]
	v_mov_b64_e32 v[0:1], s[12:13]
	v_mov_b64_e32 v[2:3], s[14:15]
	v_mov_b64_e32 v[4:5], s[16:17]
	v_mov_b64_e32 v[6:7], s[18:19]
	v_mov_b64_e32 v[8:9], s[20:21]
	v_mov_b64_e32 v[10:11], s[22:23]
	v_mov_b64_e32 v[12:13], s[24:25]
	s_waitcnt lgkmcnt(0)
	v_mfma_f32_32x32x16_bf16 v[32:47], v[66:69], v[98:101], v[32:47]
	s_nop 2
	v_max_f32_e32 v66, v17, v17
	v_max_f32_e32 v67, v16, v16
	v_max_f32_e32 v66, v67, v66
	v_max3_f32 v66, v66, v18, v19
	v_max3_f32 v66, v66, v20, v21
	v_max3_f32 v66, v66, v22, v23
	v_max3_f32 v66, v66, v24, v25
	v_max3_f32 v66, v66, v26, v27
	v_max3_f32 v66, v66, v28, v29
	v_max3_f32 v66, v66, v30, v31
	v_max3_f32 v66, v66, v32, v33
	v_max3_f32 v66, v66, v34, v35
	v_max3_f32 v66, v66, v36, v37
	v_max3_f32 v66, v66, v38, v39
	v_max3_f32 v66, v66, v40, v41
	v_max3_f32 v66, v66, v42, v43
	v_max3_f32 v66, v66, v44, v45
	v_max3_f32 v75, v66, v46, v47
	v_mov_b32_e32 v66, v75
	s_nop 1
	v_permlane32_swap_b32_e32 v75, v66
	v_max_f32_e32 v76, v66, v66
	v_add_u32_e32 v66, 0xa0, v48
	v_mad_i64_i32 v[66:67], s[10:11], v66, s71, 0
	v_add_u32_e32 v68, 0x80, v48
	v_or_b32_e32 v66, v66, v71
	v_mad_i64_i32 v[68:69], s[10:11], v68, s71, 0
	v_lshl_add_u64 v[66:67], v[66:67], 1, s[6:7]
	v_or_b32_e32 v68, v68, v71
	v_lshl_add_u64 v[68:69], v[68:69], 1, s[6:7]
	global_load_dwordx4 v[130:133], v[66:67], off offset:2048
	global_load_dwordx4 v[142:145], v[66:67], off offset:2560
	global_load_dwordx4 v[138:141], v[68:69], off offset:2048
	global_load_dwordx4 v[134:137], v[68:69], off offset:2560
	v_max_f32_e32 v66, v75, v75
	v_max_f32_e32 v66, v66, v76
	v_add_f32_e32 v67, 0x7149f2ca, v66
	s_add_i32 s6, 0, 0x10000
	v_cmp_ge_f32_e32 vcc, s72, v67
	s_waitcnt vmcnt(4)
	s_waitcnt vmcnt(7)
	ds_write_b128 v72, v[50:53] offset:16384
	s_waitcnt vmcnt(5)
	ds_write_b128 v73, v[54:57] offset:16384
	v_add_u32_e32 v50, s6, v214
	ds_write_b128 v50, v[58:61]
	v_add_u32_e32 v50, s6, v219
	s_cmp_eq_u64 vcc, exec
	s_waitcnt vmcnt(4)
; #define SBAR() __builtin_amdgcn_sched_barrier(0)
; #define SLOAD(i, k0) do { sv0[i] = *(const bf16x8*)(&Vh[(long)((k0) + sr) * LDK + sc]); sv1[i] = *(const bf16x8*)(&Vh[(long)((k0) + 32 + sr) * LDK + sc]); \
;     sk0[i] = *(const bf16x8*)(&Kh[(long)((k0) + sr) * LDK + sc]); sk1[i] = *(const bf16x8*)(&Kh[(long)((k0) + 32 + sr) * LDK + sc]); } while (0)
; #define SWRITE(off, i) do { *(bf16x8*)((char*)V_lds + (off) + vst0) = sv0[i];          \
;     *(bf16x8*)((char*)V_lds + (off) + vst1) = sv1[i]; int kc = sc * 2;               \
;     *(bf16x8*)((char*)K_lds + (off) + KSWZ(sr, kc)) = sk0[i];                       \
;     *(bf16x8*)((char*)K_lds + (off) + KSWZ(32 + sr, kc)) = sk1[i]; } while (0)
; #define SWAIT() asm volatile("s_waitcnt vmcnt(4)" ::: "memory")
; __device__ __forceinline__ void attn_dense_body(const bf16_t* __restrict__ Qb, const bf16_t* __restrict__ Kh, const bf16_t* __restrict__ Vh,
;                                                 bf16_t* __restrict__ Ob, int seq, char* lds, int dry) {
;     ...
;     qkt(pA0, pA1, K_lds, qr, r32, hi); partialSM(pA0, pA1, m_reg, mnA, alA);
;     SLOAD(1, KVBLK); if (2 < NT) SLOAD(0, 2 * KVBLK);
;     SWAIT(); SWRITE((int)SHM_K, 1); __syncthreads();
;     int oq = (int)SHM_K, ov = 0, ow = 2 * (int)SHM_K;
;     for (int j = 1; j + 1 < NT; j += 2) {
;         SBAR(); qkt(pB0, pB1, (bf16_t*)((char*)K_lds + oq), qr, r32, hi);
;         finishSM(pA0, pA1, alA, l_reg, pa0, pa1, pa2, pa3); SBAR();
	ds_write_b128 v50, v[62:65]
	v_max_f32_e32 v50, 0xf149f2ca, v66
	s_cselect_b64 vcc, -1, 0
	v_cndmask_b32_e32 v166, v50, v198, vcc
	v_sub_f32_e32 v51, 0xf149f2ca, v50
	v_mul_f32_e32 v50, 0xbe0293ee, v166
	v_fmamk_f32 v16, v16, 0x3e0293ee, v50
	v_mov_b32_e32 v163, v16
	v_fmamk_f32 v16, v17, 0x3e0293ee, v50
	v_mov_b32_e32 v177, v16
	v_fmamk_f32 v16, v18, 0x3e0293ee, v50
	v_mov_b32_e32 v164, v16
	v_fmamk_f32 v16, v19, 0x3e0293ee, v50
	v_exp_f32_e32 v229, v16
	v_fmamk_f32 v16, v20, 0x3e0293ee, v50
	v_mov_b32_e32 v176, v16
	v_fmamk_f32 v16, v21, 0x3e0293ee, v50
	v_exp_f32_e32 v230, v16
	v_fmamk_f32 v16, v22, 0x3e0293ee, v50
	v_mov_b32_e32 v165, v16
	v_fmamk_f32 v16, v23, 0x3e0293ee, v50
	v_mov_b32_e32 v175, v16
	v_fmamk_f32 v16, v24, 0x3e0293ee, v50
	v_mov_b32_e32 v171, v16
	v_fmamk_f32 v16, v25, 0x3e0293ee, v50
	v_mov_b32_e32 v173, v16
	v_fmamk_f32 v16, v26, 0x3e0293ee, v50
	v_mul_f32_e32 v51, 0x3e0293ee, v51
	v_mov_b32_e32 v172, v16
	v_fmamk_f32 v16, v27, 0x3e0293ee, v50
	v_exp_f32_e32 v51, v51
	v_mov_b32_e32 v174, v16
	v_fmamk_f32 v16, v28, 0x3e0293ee, v50
	v_mov_b32_e32 v167, v16
	v_fmamk_f32 v16, v29, 0x3e0293ee, v50
	v_mov_b32_e32 v169, v16
	v_fmamk_f32 v16, v30, 0x3e0293ee, v50
	v_mov_b64_e32 v[14:15], s[26:27]
	s_mov_b32 s20, 0x3e0293ee
	v_mov_b32_e32 v168, v16
	v_lshl_add_u64 v[16:17], v[48:49], 0, s[8:9]
	v_pk_fma_f32 v[146:147], v[46:47], s[20:21], v[50:51] op_sel_hi:[1,0,0]
	v_pk_fma_f32 v[148:149], v[44:45], s[20:21], v[50:51] op_sel_hi:[1,0,0]
	v_pk_fma_f32 v[150:151], v[42:43], s[20:21], v[50:51] op_sel_hi:[1,0,0]
	v_pk_fma_f32 v[152:153], v[40:41], s[20:21], v[50:51] op_sel_hi:[1,0,0]
	v_pk_fma_f32 v[154:155], v[38:39], s[20:21], v[50:51] op_sel_hi:[1,0,0]
	v_pk_fma_f32 v[156:157], v[36:37], s[20:21], v[50:51] op_sel_hi:[1,0,0]
	v_pk_fma_f32 v[158:159], v[34:35], s[20:21], v[50:51] op_sel_hi:[1,0,0]
	v_pk_fma_f32 v[160:161], v[32:33], s[20:21], v[50:51] op_sel_hi:[1,0,0]
	v_fmac_f32_e32 v50, 0x3e0293ee, v31
	v_mad_u64_u32 v[18:19], s[8:9], v16, s70, 0
	v_and_b32_e32 v16, 15, v70
	v_mov_b32_e32 v170, v50
	v_lshlrev_b32_e32 v16, 4, v16
	v_mad_i32_i24 v17, v17, s70, v19
	v_or3_b32 v16, v18, s39, v16
	v_cndmask_b32_e64 v225, v51, 1.0, vcc
	v_lshl_add_u64 v[180:181], s[2:3], 0, v[16:17]
	v_mov_b64_e32 v[62:63], v[14:15]
	v_mov_b64_e32 v[46:47], v[14:15]
	v_mov_b64_e32 v[30:31], v[14:15]
	v_cmp_gt_u32_e64 s[6:7], 32, v74
	s_mov_b32 s8, 0x8000
	v_mov_b64_e32 v[60:61], v[12:13]
	v_mov_b64_e32 v[58:59], v[10:11]
	v_mov_b64_e32 v[56:57], v[8:9]
	v_mov_b64_e32 v[54:55], v[6:7]
	v_mov_b64_e32 v[52:53], v[4:5]
	v_mov_b64_e32 v[50:51], v[2:3]
	v_mov_b64_e32 v[48:49], v[0:1]
	v_mov_b64_e32 v[44:45], v[12:13]
	v_mov_b64_e32 v[42:43], v[10:11]
	v_mov_b64_e32 v[40:41], v[8:9]
	v_mov_b64_e32 v[38:39], v[6:7]
	v_mov_b64_e32 v[36:37], v[4:5]
	v_mov_b64_e32 v[34:35], v[2:3]
	v_mov_b64_e32 v[32:33], v[0:1]
	v_mov_b64_e32 v[28:29], v[12:13]
	v_mov_b64_e32 v[26:27], v[10:11]
	v_mov_b64_e32 v[24:25], v[8:9]
	v_mov_b64_e32 v[22:23], v[6:7]
	v_mov_b64_e32 v[20:21], v[4:5]
	v_mov_b64_e32 v[18:19], v[2:3]
	v_mov_b64_e32 v[16:17], v[0:1]
	v_exp_f32_e32 v146, v146
	v_exp_f32_e32 v147, v147
	v_exp_f32_e32 v148, v148
	v_exp_f32_e32 v149, v149
	v_exp_f32_e32 v150, v150
	v_exp_f32_e32 v151, v151
	v_exp_f32_e32 v152, v152
	v_exp_f32_e32 v153, v153
	v_exp_f32_e32 v154, v154
	v_exp_f32_e32 v155, v155
	v_exp_f32_e32 v156, v156
	v_exp_f32_e32 v157, v157
	v_exp_f32_e32 v158, v158
	v_exp_f32_e32 v159, v159
	v_exp_f32_e32 v160, v160
	v_exp_f32_e32 v161, v161
	s_waitcnt lgkmcnt(0)
	s_barrier
.LBB0_269:
	s_mov_b32 s13, s12
	s_mov_b32 s12, s8
	s_add_i32 s8, s37, 0
	v_add_u32_e32 v71, s8, v220
	ds_read_b128 v[64:67], v71 offset:49152
	ds_read_b128 v[68:71], v71 offset:57344
	v_add_u32_e32 v239, s8, v222
	ds_read_b128 v[232:235], v239 offset:49152
	ds_read_b128 v[236:239], v239 offset:57344
	v_add_u32_e32 v247, s8, v221
	ds_read_b128 v[240:243], v247 offset:49152
	ds_read_b128 v[244:247], v247 offset:57344
	s_waitcnt lgkmcnt(5)
	v_mfma_f32_32x32x16_bf16 v[80:95], v[64:67], v[126:129], 0
	v_exp_f32_e32 v163, v163
	v_exp_f32_e32 v177, v177
	v_exp_f32_e32 v164, v164
	v_exp_f32_e32 v176, v176
	s_waitcnt lgkmcnt(4)
	v_mfma_f32_32x32x16_bf16 v[64:79], v[68:71], v[126:129], 0
	v_exp_f32_e32 v165, v165
	v_exp_f32_e32 v175, v175
	v_exp_f32_e32 v171, v171
	v_exp_f32_e32 v173, v173
	s_waitcnt lgkmcnt(3)
	v_mfma_f32_32x32x16_bf16 v[80:95], v[232:235], v[122:125], v[80:95]
	v_exp_f32_e32 v172, v172
	v_exp_f32_e32 v174, v174
	v_exp_f32_e32 v167, v167
	v_exp_f32_e32 v169, v169
	s_waitcnt lgkmcnt(2)
	v_mfma_f32_32x32x16_bf16 v[64:79], v[236:239], v[122:125], v[64:79]
	v_add_u32_e32 v239, s8, v218
	ds_read_b128 v[232:235], v239 offset:49152
	ds_read_b128 v[236:239], v239 offset:57344
	v_exp_f32_e32 v168, v168
	v_exp_f32_e32 v170, v170
	v_add_f32_e32 v162, 0, v163
	v_add_f32_e32 v162, v177, v162
	s_waitcnt lgkmcnt(3)
	v_mfma_f32_32x32x16_bf16 v[80:95], v[240:243], v[118:121], v[80:95]
	v_add_f32_e32 v162, v164, v162
	v_add_f32_e32 v162, v229, v162
	v_add_f32_e32 v162, v176, v162
	v_add_f32_e32 v162, v230, v162
	s_waitcnt lgkmcnt(2)
	v_mfma_f32_32x32x16_bf16 v[64:79], v[244:247], v[118:121], v[64:79]
	v_add_u32_e32 v247, s8, v215
	ds_read_b128 v[240:243], v247 offset:49152
	ds_read_b128 v[244:247], v247 offset:57344
	v_add_f32_e32 v162, v165, v162
	v_add_f32_e32 v162, v175, v162
	v_add_f32_e32 v162, v171, v162
	v_add_f32_e32 v162, v173, v162
	s_waitcnt lgkmcnt(3)
	v_mfma_f32_32x32x16_bf16 v[80:95], v[232:235], v[114:117], v[80:95]
	v_add_f32_e32 v162, v172, v162
	v_add_f32_e32 v162, v174, v162
	v_add_f32_e32 v162, v167, v162
	v_add_f32_e32 v162, v169, v162
	s_waitcnt lgkmcnt(2)
; #define SBAR() __builtin_amdgcn_sched_barrier(0)
; #define SLOAD(i, k0) do { sv0[i] = *(const bf16x8*)(&Vh[(long)((k0) + sr) * LDK + sc]); sv1[i] = *(const bf16x8*)(&Vh[(long)((k0) + 32 + sr) * LDK + sc]); \
;     sk0[i] = *(const bf16x8*)(&Kh[(long)((k0) + sr) * LDK + sc]); sk1[i] = *(const bf16x8*)(&Kh[(long)((k0) + 32 + sr) * LDK + sc]); } while (0)
; #define SWRITE(off, i) do { *(bf16x8*)((char*)V_lds + (off) + vst0) = sv0[i];          \
;     *(bf16x8*)((char*)V_lds + (off) + vst1) = sv1[i]; int kc = sc * 2;               \
;     *(bf16x8*)((char*)K_lds + (off) + KSWZ(sr, kc)) = sk0[i];                       \
;     *(bf16x8*)((char*)K_lds + (off) + KSWZ(32 + sr, kc)) = sk1[i]; } while (0)
; #define SWAIT() asm volatile("s_waitcnt vmcnt(4)" ::: "memory")
; __device__ __forceinline__ void finishSM(f32x16& p0, f32x16& p1, float alpha, float& l_reg, bf16x8& pa0, bf16x8& pa1, bf16x8& pa2, bf16x8& pa3) {
;     ...
;     PK4(p0, 0, pa0); PK4(p0, 8, pa1); PK4(p1, 0, pa2); PK4(p1, 8, pa3);
; __device__ __forceinline__ void attn_dense_body(const bf16_t* __restrict__ Qb, const bf16_t* __restrict__ Kh, const bf16_t* __restrict__ Vh,
;                                                 bf16_t* __restrict__ Ob, int seq, char* lds, int dry) {
;     ...
;         SBAR(); qkt(pB0, pB1, (bf16_t*)((char*)K_lds + oq), qr, r32, hi);
;         finishSM(pA0, pA1, alA, l_reg, pa0, pa1, pa2, pa3); SBAR();
;         SLOAD(1, (j + 2) * KVBLK); SBAR();
;         pv_d0(o, vb0 + ov, pa0, pa1, pa2, pa3); partialSM(pB0, pB1, m_reg, mnB, alB);
;         SWAIT(); SWRITE(ow, 0);
	v_mfma_f32_32x32x16_bf16 v[64:79], v[236:239], v[114:117], v[64:79]
	v_add_u32_e32 v239, s8, v213
	ds_read_b128 v[232:235], v239 offset:49152
	ds_read_b128 v[236:239], v239 offset:57344
	v_add_f32_e32 v162, v168, v162
	v_add_f32_e32 v162, v170, v162
	v_add_f32_e32 v162, v160, v162
	v_add_f32_e32 v162, v161, v162
	s_waitcnt lgkmcnt(3)
	v_mfma_f32_32x32x16_bf16 v[80:95], v[240:243], v[110:113], v[80:95]
	v_add_f32_e32 v162, v158, v162
	v_add_f32_e32 v162, v159, v162
	v_add_f32_e32 v162, v156, v162
	v_add_f32_e32 v162, v157, v162
	s_waitcnt lgkmcnt(2)
	v_mfma_f32_32x32x16_bf16 v[64:79], v[244:247], v[110:113], v[64:79]
	v_add_u32_e32 v247, s8, v223
	ds_read_b128 v[240:243], v247 offset:49152
	ds_read_b128 v[244:247], v247 offset:57344
	v_add_f32_e32 v162, v154, v162
	v_add_f32_e32 v162, v155, v162
	v_add_f32_e32 v162, v152, v162
	v_add_f32_e32 v162, v153, v162
	s_waitcnt lgkmcnt(3)
	v_mfma_f32_32x32x16_bf16 v[80:95], v[232:235], v[106:109], v[80:95]
	v_add_f32_e32 v162, v150, v162
	v_add_f32_e32 v162, v151, v162
	v_add_f32_e32 v162, v148, v162
	v_add_f32_e32 v162, v149, v162
	s_waitcnt lgkmcnt(2)
	v_mfma_f32_32x32x16_bf16 v[64:79], v[236:239], v[106:109], v[64:79]
	v_add_u32_e32 v239, s8, v224
	ds_read_b128 v[232:235], v239 offset:49152
	ds_read_b128 v[236:239], v239 offset:57344
	v_add_f32_e32 v162, v146, v162
	v_add_f32_e32 v226, v147, v162
	v_mov_b32_e32 v227, v226
	v_cvt_pk_bf16_f32 v162, v163, v177
	s_waitcnt lgkmcnt(3)
	v_mfma_f32_32x32x16_bf16 v[80:95], v[240:243], v[102:105], v[80:95]
	v_cvt_pk_bf16_f32 v163, v164, v229
	v_cvt_pk_bf16_f32 v164, v176, v230
	v_cvt_pk_bf16_f32 v165, v165, v175
	v_cvt_pk_bf16_f32 v228, v171, v173
	s_waitcnt lgkmcnt(2)
	v_mfma_f32_32x32x16_bf16 v[64:79], v[244:247], v[102:105], v[64:79]
	v_cvt_pk_bf16_f32 v229, v172, v174
	v_cvt_pk_bf16_f32 v230, v167, v169
	v_permlane32_swap_b32_e32 v226, v227
	v_cvt_pk_bf16_f32 v231, v168, v170
	s_waitcnt lgkmcnt(1)
	v_mfma_f32_32x32x16_bf16 v[80:95], v[232:235], v[98:101], v[80:95]
	v_cvt_pk_bf16_f32 v168, v160, v161
	v_cvt_pk_bf16_f32 v169, v158, v159
	v_cvt_pk_bf16_f32 v170, v156, v157
	v_cvt_pk_bf16_f32 v171, v154, v155
	s_waitcnt lgkmcnt(0)
	v_mfma_f32_32x32x16_bf16 v[64:79], v[236:239], v[98:101], v[64:79]
	v_cvt_pk_bf16_f32 v172, v152, v153
	v_cvt_pk_bf16_f32 v173, v150, v151
	v_cvt_pk_bf16_f32 v174, v148, v149
	v_cvt_pk_bf16_f32 v175, v146, v147
	s_mov_b32 s8, 0xfffb8000
	v_add_co_u32_e32 v150, vcc, s8, v180
	s_mov_b32 s8, 0xfffd0000
	s_nop 0
	v_addc_co_u32_e32 v151, vcc, -1, v181, vcc
	v_add_co_u32_e32 v154, vcc, s8, v180
	s_nop 1
	v_addc_co_u32_e32 v155, vcc, -1, v181, vcc
	global_load_dwordx4 v[146:149], v[150:151], off
	s_nop 0
	global_load_dwordx4 v[150:153], v[150:151], off offset:-512
	s_nop 0
	global_load_dwordx4 v[158:161], v[154:155], off
	s_nop 0
	global_load_dwordx4 v[154:157], v[154:155], off offset:-512
	v_add_u32_e32 v211, s13, v212
	ds_read_b64_tr_b16 v[232:233], v211 offset:0x0
	ds_read_b64_tr_b16 v[234:235], v211 offset:0x800
	ds_read_b64_tr_b16 v[236:237], v211 offset:0x1000
	ds_read_b64_tr_b16 v[238:239], v211 offset:0x1800
	ds_read_b64_tr_b16 v[240:241], v211 offset:0x2000
	ds_read_b64_tr_b16 v[242:243], v211 offset:0x2800
	ds_read_b64_tr_b16 v[244:245], v211 offset:0x3000
	ds_read_b64_tr_b16 v[246:247], v211 offset:0x3800
	s_waitcnt lgkmcnt(0)
	s_nop 0
	v_mfma_f32_32x32x16_bf16 v[0:15], v[162:165], v[232:235], v[0:15]
	ds_read_b64_tr_b16 v[232:233], v211 offset:0x200
	ds_read_b64_tr_b16 v[234:235], v211 offset:0xa00
	s_add_i32 s14, s12, 0
	s_waitcnt vmcnt(4)
	v_add_u32_e32 v253, s14, v216
	ds_write_b128 v253, v[134:137]
	v_max_f32_e32 v248, v81, v81
	v_max_f32_e32 v249, v80, v80
	v_max_f32_e32 v248, v249, v248
	v_max3_f32 v248, v248, v82, v83
	v_max3_f32 v248, v248, v84, v85
	v_mfma_f32_32x32x16_bf16 v[0:15], v[228:231], v[236:239], v[0:15]
	ds_read_b64_tr_b16 v[236:237], v211 offset:0x1200
	ds_read_b64_tr_b16 v[238:239], v211 offset:0x1a00
	v_add_u32_e32 v253, s14, v217
	ds_write_b128 v253, v[142:145]
	v_max3_f32 v248, v248, v86, v87
	v_max3_f32 v248, v248, v88, v89
	v_max3_f32 v248, v248, v90, v91
	v_max3_f32 v248, v248, v92, v93
	v_max3_f32 v248, v248, v94, v95
	v_mfma_f32_32x32x16_bf16 v[0:15], v[168:171], v[240:243], v[0:15]
	ds_read_b64_tr_b16 v[240:241], v211 offset:0x2200
	ds_read_b64_tr_b16 v[242:243], v211 offset:0x2a00
	v_add_u32_e32 v253, s14, v214
	ds_write_b128 v253, v[138:141] offset:49152
	v_max3_f32 v248, v248, v64, v65
	v_max3_f32 v248, v248, v66, v67
	v_max3_f32 v248, v248, v68, v69
	v_max3_f32 v248, v248, v70, v71
	v_max3_f32 v248, v248, v72, v73
	v_mfma_f32_32x32x16_bf16 v[0:15], v[172:175], v[244:247], v[0:15]
	ds_read_b64_tr_b16 v[244:245], v211 offset:0x3200
	ds_read_b64_tr_b16 v[246:247], v211 offset:0x3a00
	v_add_u32_e32 v253, s14, v219
	ds_write_b128 v253, v[130:133] offset:49152
	v_max3_f32 v248, v248, v74, v75
	v_max3_f32 v248, v248, v76, v77
	v_max3_f32 v248, v248, v78, v79
	v_mov_b32_e32 v249, v248
	s_waitcnt lgkmcnt(0)
	v_mfma_f32_32x32x16_bf16 v[48:63], v[162:165], v[232:235], v[48:63]
	ds_read_b64_tr_b16 v[232:233], v211 offset:0x400
	ds_read_b64_tr_b16 v[234:235], v211 offset:0xc00
	v_permlane32_swap_b32_e32 v248, v249
	v_max_f32_e32 v249, v249, v249
	v_max_f32_e32 v248, v248, v248
	v_max_f32_e32 v248, v248, v249
	v_mfma_f32_32x32x16_bf16 v[48:63], v[228:231], v[236:239], v[48:63]
	ds_read_b64_tr_b16 v[236:237], v211 offset:0x1400
	ds_read_b64_tr_b16 v[238:239], v211 offset:0x1c00
	v_sub_f32_e32 v249, v248, v166
	v_cmp_ge_f32_e32 vcc, s72, v249
	v_max_f32_e32 v249, v166, v166
	v_max_f32_e32 v248, v249, v248
	v_sub_f32_e32 v249, v166, v248
	v_mfma_f32_32x32x16_bf16 v[48:63], v[168:171], v[240:243], v[48:63]
	ds_read_b64_tr_b16 v[240:241], v211 offset:0x2400
	ds_read_b64_tr_b16 v[242:243], v211 offset:0x2c00
	v_mul_f32_e32 v249, 0x3e0293ee, v249
	v_exp_f32_e32 v249, v249
	v_mfma_f32_32x32x16_bf16 v[48:63], v[172:175], v[244:247], v[48:63]
	ds_read_b64_tr_b16 v[244:245], v211 offset:0x3400
	ds_read_b64_tr_b16 v[246:247], v211 offset:0x3c00
	s_cmp_eq_u64 vcc, exec
	s_cselect_b64 s[8:9], -1, 0
	s_nop 0
	v_cndmask_b32_e64 v167, v249, 1.0, s[8:9]
	v_cndmask_b32_e64 v176, v248, v166, s[8:9]
	v_mul_f32_e32 v177, 0xbe0293ee, v176
	s_waitcnt lgkmcnt(0)
; #define SWRITE(off, i) do { *(bf16x8*)((char*)V_lds + (off) + vst0) = sv0[i];          \
;     *(bf16x8*)((char*)V_lds + (off) + vst1) = sv1[i]; int kc = sc * 2;               \
;     *(bf16x8*)((char*)K_lds + (off) + KSWZ(sr, kc)) = sk0[i];                       \
;     *(bf16x8*)((char*)K_lds + (off) + KSWZ(32 + sr, kc)) = sk1[i]; } while (0)
; #define SWAIT() asm volatile("s_waitcnt vmcnt(4)" ::: "memory")
; #define RESC(a) do { if (__any((a) < 1.f)) { if (hi == 0) al_l[r32] = (a); asm volatile("s_waitcnt lgkmcnt(0)" ::: "memory"); \
;     _Pragma("unroll") for (int d = 0; d < 4; ++d) _Pragma("unroll") for (int r = 0; r < 16; ++r) o[d][r] *= al_l[crow(r, hi)]; } } while (0)
; __device__ __forceinline__ void attn_dense_body(const bf16_t* __restrict__ Qb, const bf16_t* __restrict__ Kh, const bf16_t* __restrict__ Vh,
;                                                 bf16_t* __restrict__ Ob, int seq, char* lds, int dry) {
;     ...
;         pv_d0(o, vb0 + ov, pa0, pa1, pa2, pa3); partialSM(pB0, pB1, m_reg, mnB, alB);
;         SWAIT(); SWRITE(ow, 0);
;         RESC(alB); __syncthreads();
	v_mfma_f32_32x32x16_bf16 v[32:47], v[162:165], v[232:235], v[32:47]
	ds_read_b64_tr_b16 v[232:233], v211 offset:0x600
	ds_read_b64_tr_b16 v[234:235], v211 offset:0xe00
	v_fmamk_f32 v250, v92, 0x3e0293ee, v177
	v_fmamk_f32 v251, v93, 0x3e0293ee, v177
	v_fmamk_f32 v252, v94, 0x3e0293ee, v177
	v_fmamk_f32 v253, v95, 0x3e0293ee, v177
	v_mfma_f32_32x32x16_bf16 v[32:47], v[228:231], v[236:239], v[32:47]
	ds_read_b64_tr_b16 v[236:237], v211 offset:0x1600
	ds_read_b64_tr_b16 v[238:239], v211 offset:0x1e00
	v_fmamk_f32 v248, v90, 0x3e0293ee, v177
	v_fmamk_f32 v249, v91, 0x3e0293ee, v177
	v_mfma_f32_32x32x16_bf16 v[32:47], v[168:171], v[240:243], v[32:47]
	ds_read_b64_tr_b16 v[240:241], v211 offset:0x2600
	ds_read_b64_tr_b16 v[242:243], v211 offset:0x2e00
	v_exp_f32_e32 v250, v250
	v_exp_f32_e32 v251, v251
	v_exp_f32_e32 v252, v252
	v_mfma_f32_32x32x16_bf16 v[32:47], v[172:175], v[244:247], v[32:47]
	ds_read_b64_tr_b16 v[244:245], v211 offset:0x3600
	ds_read_b64_tr_b16 v[246:247], v211 offset:0x3e00
	v_exp_f32_e32 v253, v253
	v_exp_f32_e32 v248, v248
	v_exp_f32_e32 v249, v249
	s_waitcnt lgkmcnt(0)
	v_mfma_f32_32x32x16_bf16 v[16:31], v[162:165], v[232:235], v[16:31]
	v_fmamk_f32 v232, v73, 0x3e0293ee, v177
	v_fmamk_f32 v233, v74, 0x3e0293ee, v177
	v_fmamk_f32 v234, v75, 0x3e0293ee, v177
	v_fmamk_f32 v235, v76, 0x3e0293ee, v177
	v_mfma_f32_32x32x16_bf16 v[16:31], v[228:231], v[236:239], v[16:31]
	v_fmamk_f32 v238, v80, 0x3e0293ee, v177
	v_fmamk_f32 v239, v81, 0x3e0293ee, v177
	v_fmamk_f32 v236, v77, 0x3e0293ee, v177
	v_fmamk_f32 v237, v78, 0x3e0293ee, v177
	v_fmamk_f32 v230, v71, 0x3e0293ee, v177
	v_fmamk_f32 v231, v72, 0x3e0293ee, v177
	v_mfma_f32_32x32x16_bf16 v[16:31], v[168:171], v[240:243], v[16:31]
	v_fmamk_f32 v240, v82, 0x3e0293ee, v177
	v_fmamk_f32 v241, v83, 0x3e0293ee, v177
	v_fmamk_f32 v242, v84, 0x3e0293ee, v177
	v_fmamk_f32 v243, v85, 0x3e0293ee, v177
	v_fmamk_f32 v170, v79, 0x3e0293ee, v177
	v_fmamk_f32 v171, v64, 0x3e0293ee, v177
	v_mfma_f32_32x32x16_bf16 v[16:31], v[172:175], v[244:247], v[16:31]
	v_fmamk_f32 v244, v86, 0x3e0293ee, v177
	v_fmamk_f32 v245, v87, 0x3e0293ee, v177
	v_fmamk_f32 v246, v88, 0x3e0293ee, v177
	v_fmamk_f32 v247, v89, 0x3e0293ee, v177
	v_fmamk_f32 v172, v65, 0x3e0293ee, v177
	v_fmamk_f32 v173, v66, 0x3e0293ee, v177
	v_fmamk_f32 v174, v67, 0x3e0293ee, v177
	v_fmamk_f32 v175, v68, 0x3e0293ee, v177
	v_mov_b32_e32 v228, v167
	s_nop 0
	v_cmp_gt_f32_e32 vcc, 1.0, v228
	s_cbranch_vccz .LBB0_273
	s_and_saveexec_b64 s[10:11], s[6:7]
	ds_write_b32 v209, v228 offset:128
	s_or_b64 exec, exec, s[10:11]
	s_waitcnt lgkmcnt(0)
	v_add_u32_e32 v163, v179, v96
	ds_read_b128 v[80:83], v163 offset:224
	ds_read_b128 v[84:87], v163 offset:192
	ds_read_b128 v[88:91], v163 offset:160
	ds_read_b128 v[92:95], v163 offset:128
	s_waitcnt lgkmcnt(3)
	v_pk_mul_f32 v[12:13], v[12:13], v[80:81]
	s_waitcnt lgkmcnt(2)
	v_pk_mul_f32 v[8:9], v[8:9], v[84:85]
	s_waitcnt lgkmcnt(1)
	v_pk_mul_f32 v[4:5], v[4:5], v[88:89]
	v_pk_mul_f32 v[14:15], v[14:15], v[82:83]
	v_pk_mul_f32 v[10:11], v[10:11], v[86:87]
	v_pk_mul_f32 v[6:7], v[6:7], v[90:91]
	s_waitcnt lgkmcnt(0)
	v_pk_mul_f32 v[2:3], v[2:3], v[94:95]
	v_pk_mul_f32 v[0:1], v[0:1], v[92:93]
	v_pk_mul_f32 v[60:61], v[60:61], v[80:81]
	v_pk_mul_f32 v[56:57], v[56:57], v[84:85]
	v_pk_mul_f32 v[52:53], v[52:53], v[88:89]
	v_pk_mul_f32 v[62:63], v[62:63], v[82:83]
	v_pk_mul_f32 v[58:59], v[58:59], v[86:87]
	v_pk_mul_f32 v[54:55], v[54:55], v[90:91]
	v_pk_mul_f32 v[50:51], v[50:51], v[94:95]
	v_pk_mul_f32 v[48:49], v[48:49], v[92:93]
	v_pk_mul_f32 v[44:45], v[44:45], v[80:81]
	v_pk_mul_f32 v[40:41], v[40:41], v[84:85]
	v_pk_mul_f32 v[36:37], v[36:37], v[88:89]
	v_pk_mul_f32 v[46:47], v[46:47], v[82:83]
	v_pk_mul_f32 v[42:43], v[42:43], v[86:87]
	v_pk_mul_f32 v[38:39], v[38:39], v[90:91]
	v_pk_mul_f32 v[34:35], v[34:35], v[94:95]
	v_pk_mul_f32 v[32:33], v[32:33], v[92:93]
	v_pk_mul_f32 v[28:29], v[28:29], v[80:81]
	v_pk_mul_f32 v[24:25], v[24:25], v[84:85]
	v_pk_mul_f32 v[20:21], v[20:21], v[88:89]
	v_pk_mul_f32 v[30:31], v[30:31], v[82:83]
	v_pk_mul_f32 v[26:27], v[26:27], v[86:87]
	v_pk_mul_f32 v[22:23], v[22:23], v[90:91]
	v_pk_mul_f32 v[18:19], v[18:19], v[94:95]
	v_pk_mul_f32 v[16:17], v[16:17], v[92:93]
; #define SBAR() __builtin_amdgcn_sched_barrier(0)
; #define SLOAD(i, k0) do { sv0[i] = *(const bf16x8*)(&Vh[(long)((k0) + sr) * LDK + sc]); sv1[i] = *(const bf16x8*)(&Vh[(long)((k0) + 32 + sr) * LDK + sc]); \
;     sk0[i] = *(const bf16x8*)(&Kh[(long)((k0) + sr) * LDK + sc]); sk1[i] = *(const bf16x8*)(&Kh[(long)((k0) + 32 + sr) * LDK + sc]); } while (0)
; #define RESC(a) do { if (__any((a) < 1.f)) { if (hi == 0) al_l[r32] = (a); asm volatile("s_waitcnt lgkmcnt(0)" ::: "memory"); \
;     _Pragma("unroll") for (int d = 0; d < 4; ++d) _Pragma("unroll") for (int r = 0; r < 16; ++r) o[d][r] *= al_l[crow(r, hi)]; } } while (0)
; __device__ __forceinline__ void finishSM(f32x16& p0, f32x16& p1, float alpha, float& l_reg, bf16x8& pa0, bf16x8& pa1, bf16x8& pa2, bf16x8& pa3) {
;     ...
;     PK4(p0, 0, pa0); PK4(p0, 8, pa1); PK4(p1, 0, pa2); PK4(p1, 8, pa3);
; __device__ __forceinline__ void attn_dense_body(const bf16_t* __restrict__ Qb, const bf16_t* __restrict__ Kh, const bf16_t* __restrict__ Vh,
;                                                 bf16_t* __restrict__ Ob, int seq, char* lds, int dry) {
;     ...
;         RESC(alB); __syncthreads();
;         { const int t_ = ov; ov = oq; oq = ow; ow = t_; }
;         SBAR(); qkt(pA0, pA1, (bf16_t*)((char*)K_lds + oq), qr, r32, hi);
;         finishSM(pB0, pB1, alB, l_reg, pa0, pa1, pa2, pa3); SBAR();
;         if (j + 3 < NT) SLOAD(0, (j + 3) * KVBLK); SBAR();
.LBB0_273:
	v_mov_b32_e32 v229, v176
	v_fmamk_f32 v176, v69, 0x3e0293ee, v177
	v_fmac_f32_e32 v177, 0x3e0293ee, v70
	s_waitcnt lgkmcnt(0)
	s_barrier
	v_add_u32_e32 v71, s14, v220
	ds_read_b128 v[64:67], v71 offset:49152
	ds_read_b128 v[68:71], v71 offset:57344
	v_add_u32_e32 v137, s14, v222
	ds_read_b128 v[130:133], v137 offset:49152
	ds_read_b128 v[134:137], v137 offset:57344
	v_add_u32_e32 v145, s14, v221
	ds_read_b128 v[138:141], v145 offset:49152
	ds_read_b128 v[142:145], v145 offset:57344
	s_waitcnt lgkmcnt(5)
	v_mfma_f32_32x32x16_bf16 v[80:95], v[64:67], v[126:129], 0
	v_exp_f32_e32 v238, v238
	v_exp_f32_e32 v239, v239
	v_exp_f32_e32 v240, v240
	v_exp_f32_e32 v241, v241
	v_exp_f32_e32 v242, v242
	s_waitcnt lgkmcnt(4)
	v_mfma_f32_32x32x16_bf16 v[64:79], v[68:71], v[126:129], 0
	v_exp_f32_e32 v243, v243
	v_exp_f32_e32 v244, v244
	v_exp_f32_e32 v245, v245
	v_exp_f32_e32 v246, v246
	v_exp_f32_e32 v247, v247
	s_waitcnt lgkmcnt(3)
	v_mfma_f32_32x32x16_bf16 v[80:95], v[130:133], v[122:125], v[80:95]
	v_add_f32_e32 v162, 0, v238
	v_exp_f32_e32 v171, v171
	v_add_f32_e32 v162, v239, v162
	v_exp_f32_e32 v172, v172
	v_add_f32_e32 v162, v240, v162
	s_waitcnt lgkmcnt(2)
	v_mfma_f32_32x32x16_bf16 v[64:79], v[134:137], v[122:125], v[64:79]
	v_add_u32_e32 v137, s14, v218
	ds_read_b128 v[130:133], v137 offset:49152
	ds_read_b128 v[134:137], v137 offset:57344
	v_exp_f32_e32 v173, v173
	v_add_f32_e32 v162, v241, v162
	v_exp_f32_e32 v174, v174
	v_add_f32_e32 v162, v242, v162
	v_exp_f32_e32 v175, v175
	s_waitcnt lgkmcnt(3)
	v_mfma_f32_32x32x16_bf16 v[80:95], v[138:141], v[118:121], v[80:95]
	v_add_f32_e32 v162, v243, v162
	v_exp_f32_e32 v176, v176
	v_add_f32_e32 v162, v244, v162
	v_exp_f32_e32 v177, v177
	v_add_f32_e32 v162, v245, v162
	s_waitcnt lgkmcnt(2)
	v_mfma_f32_32x32x16_bf16 v[64:79], v[142:145], v[118:121], v[64:79]
	v_add_u32_e32 v145, s14, v215
	ds_read_b128 v[138:141], v145 offset:49152
	ds_read_b128 v[142:145], v145 offset:57344
	v_exp_f32_e32 v230, v230
	v_add_f32_e32 v162, v246, v162
	v_exp_f32_e32 v188, v231
	v_add_f32_e32 v162, v247, v162
	v_exp_f32_e32 v186, v232
	s_waitcnt lgkmcnt(3)
	v_mfma_f32_32x32x16_bf16 v[80:95], v[130:133], v[114:117], v[80:95]
	v_add_f32_e32 v162, v248, v162
	v_exp_f32_e32 v233, v233
	v_add_f32_e32 v162, v249, v162
	v_exp_f32_e32 v234, v234
	v_add_f32_e32 v162, v250, v162
	s_waitcnt lgkmcnt(2)
	v_mfma_f32_32x32x16_bf16 v[64:79], v[134:137], v[114:117], v[64:79]
	v_add_u32_e32 v137, s14, v213
	ds_read_b128 v[130:133], v137 offset:49152
	ds_read_b128 v[134:137], v137 offset:57344
	v_exp_f32_e32 v235, v235
	v_add_f32_e32 v162, v251, v162
	v_exp_f32_e32 v236, v236
	v_add_f32_e32 v162, v252, v162
	v_exp_f32_e32 v237, v237
	s_waitcnt lgkmcnt(3)
	v_mfma_f32_32x32x16_bf16 v[80:95], v[138:141], v[110:113], v[80:95]
	v_add_f32_e32 v162, v253, v162
	v_exp_f32_e32 v194, v170
	v_add_f32_e32 v162, v171, v162
	v_add_f32_e32 v162, v172, v162
	v_add_f32_e32 v162, v173, v162
	s_waitcnt lgkmcnt(2)
	v_mfma_f32_32x32x16_bf16 v[64:79], v[142:145], v[110:113], v[64:79]
	v_add_u32_e32 v145, s14, v223
	ds_read_b128 v[138:141], v145 offset:49152
	ds_read_b128 v[142:145], v145 offset:57344
	v_add_f32_e32 v162, v174, v162
	v_add_f32_e32 v162, v175, v162
	v_add_f32_e32 v162, v176, v162
	v_add_f32_e32 v162, v177, v162
	v_add_f32_e32 v162, v230, v162
	s_waitcnt lgkmcnt(3)
	v_mfma_f32_32x32x16_bf16 v[80:95], v[130:133], v[106:109], v[80:95]
	v_add_f32_e32 v162, v188, v162
	v_add_f32_e32 v162, v186, v162
	v_add_f32_e32 v162, v233, v162
	v_add_f32_e32 v162, v234, v162
	v_add_f32_e32 v162, v235, v162
	s_waitcnt lgkmcnt(2)
	v_mfma_f32_32x32x16_bf16 v[64:79], v[134:137], v[106:109], v[64:79]
	v_add_u32_e32 v137, s14, v224
	ds_read_b128 v[130:133], v137 offset:49152
	ds_read_b128 v[134:137], v137 offset:57344
	v_add_f32_e32 v162, v236, v162
	v_add_f32_e32 v162, v237, v162
	v_add_f32_e32 v231, v194, v162
	v_mov_b32_e32 v232, v231
	v_cvt_pk_bf16_f32 v162, v238, v239
	s_waitcnt lgkmcnt(3)
	v_mfma_f32_32x32x16_bf16 v[80:95], v[138:141], v[102:105], v[80:95]
	v_cvt_pk_bf16_f32 v163, v240, v241
	v_cvt_pk_bf16_f32 v164, v242, v243
	v_cvt_pk_bf16_f32 v165, v244, v245
	v_cvt_pk_bf16_f32 v166, v246, v247
	v_cvt_pk_bf16_f32 v167, v248, v249
	s_waitcnt lgkmcnt(2)
	v_mfma_f32_32x32x16_bf16 v[64:79], v[142:145], v[102:105], v[64:79]
	v_cvt_pk_bf16_f32 v168, v250, v251
	v_cvt_pk_bf16_f32 v169, v252, v253
	v_cvt_pk_bf16_f32 v170, v171, v172
	v_cvt_pk_bf16_f32 v171, v173, v174
	s_waitcnt lgkmcnt(1)
	v_mfma_f32_32x32x16_bf16 v[80:95], v[130:133], v[98:101], v[80:95]
	v_cvt_pk_bf16_f32 v172, v175, v176
	v_cvt_pk_bf16_f32 v173, v177, v230
	v_cvt_pk_bf16_f32 v174, v188, v186
	v_cvt_pk_bf16_f32 v175, v233, v234
	s_waitcnt lgkmcnt(0)
	v_mfma_f32_32x32x16_bf16 v[64:79], v[134:137], v[98:101], v[64:79]
	v_cvt_pk_bf16_f32 v176, v235, v236
	v_cvt_pk_bf16_f32 v177, v237, v194
	s_nop 1
	v_permlane32_swap_b32_e32 v231, v232
	s_add_i32 s38, s38, 2
	s_cmp_ge_u32 s38, s36
	s_cselect_b64 s[10:11], -1, 0
	s_and_b64 vcc, exec, s[10:11]
	s_cbranch_vccnz .LBB0_275
	v_add_co_u32_e32 v130, vcc, 0xfffe8000, v180
	s_nop 1
	v_addc_co_u32_e32 v131, vcc, -1, v181, vcc
	global_load_dwordx4 v[134:137], v[130:131], off
	global_load_dwordx4 v[138:141], v[130:131], off offset:-512
	global_load_dwordx4 v[142:145], v[180:181], off
	s_nop 0
	global_load_dwordx4 v[130:133], v[180:181], off offset:-512

; #define SBAR() __builtin_amdgcn_sched_barrier(0)
; __device__ __forceinline__ void finishSM(f32x16& p0, f32x16& p1, float alpha, float& l_reg, bf16x8& pa0, bf16x8& pa1, bf16x8& pa2, bf16x8& pa3) {
;     ...
;     PK4(p0, 0, pa0); PK4(p0, 8, pa1); PK4(p1, 0, pa2); PK4(p1, 8, pa3);
; __device__ __forceinline__ void attn_dense_body(const bf16_t* __restrict__ Qb, const bf16_t* __restrict__ Kh, const bf16_t* __restrict__ Vh,
;                                                 bf16_t* __restrict__ Ob, int seq, char* lds, int dry) {
;     ...
;     SBAR(); qkt(pB0, pB1, (bf16_t*)((char*)K_lds + oq), qr, r32, hi);
;     finishSM(pA0, pA1, alA, l_reg, pa0, pa1, pa2, pa3); SBAR();
;     pv_d0(o, vb0 + ov, pa0, pa1, pa2, pa3); partialSM(pB0, pB1, m_reg, mnB, alB);
.LBB0_281:
	v_exp_f32_e32 v163, v163
	v_exp_f32_e32 v177, v177
	v_exp_f32_e32 v164, v164
	v_exp_f32_e32 v176, v176
	v_exp_f32_e32 v165, v165
	v_exp_f32_e32 v175, v175
	v_exp_f32_e32 v171, v171
	v_exp_f32_e32 v173, v173
	v_exp_f32_e32 v172, v172
	v_exp_f32_e32 v174, v174
	v_exp_f32_e32 v167, v167
	v_exp_f32_e32 v169, v169
	v_exp_f32_e32 v168, v168
	v_exp_f32_e32 v170, v170
	v_add_u32_e32 v68, s16, v220
	ds_read_b128 v[64:67], v68 offset:49152
	ds_read_b128 v[68:71], v68 offset:57344
	v_add_u32_e32 v130, s16, v222
	s_waitcnt lgkmcnt(1)
	v_mfma_f32_32x32x16_bf16 v[80:95], v[64:67], v[126:129], 0
	s_waitcnt lgkmcnt(0)
	v_mfma_f32_32x32x16_bf16 v[64:79], v[68:71], v[126:129], 0
	ds_read_b128 v[126:129], v130 offset:49152
	ds_read_b128 v[130:133], v130 offset:57344
	s_waitcnt lgkmcnt(1)
	v_mfma_f32_32x32x16_bf16 v[80:95], v[126:129], v[122:125], v[80:95]
	v_add_u32_e32 v126, s16, v221
	s_waitcnt lgkmcnt(0)
	v_mfma_f32_32x32x16_bf16 v[64:79], v[130:133], v[122:125], v[64:79]
	ds_read_b128 v[122:125], v126 offset:49152
	ds_read_b128 v[126:129], v126 offset:57344
	s_waitcnt lgkmcnt(1)
	v_mfma_f32_32x32x16_bf16 v[80:95], v[122:125], v[118:121], v[80:95]
	v_add_u32_e32 v122, s16, v218
	s_waitcnt lgkmcnt(0)
	v_mfma_f32_32x32x16_bf16 v[64:79], v[126:129], v[118:121], v[64:79]
	ds_read_b128 v[118:121], v122 offset:49152
	ds_read_b128 v[122:125], v122 offset:57344
	s_waitcnt lgkmcnt(1)
	v_mfma_f32_32x32x16_bf16 v[80:95], v[118:121], v[114:117], v[80:95]
	v_add_u32_e32 v118, s16, v215
	s_waitcnt lgkmcnt(0)
	v_mfma_f32_32x32x16_bf16 v[64:79], v[122:125], v[114:117], v[64:79]
	ds_read_b128 v[114:117], v118 offset:49152
	ds_read_b128 v[118:121], v118 offset:57344
	v_mov_b32_e32 v122, v146
	v_mov_b32_e32 v123, v147
	s_waitcnt lgkmcnt(1)
	v_mfma_f32_32x32x16_bf16 v[80:95], v[114:117], v[110:113], v[80:95]
	v_add_u32_e32 v114, s16, v213
	s_waitcnt lgkmcnt(0)
	v_mfma_f32_32x32x16_bf16 v[64:79], v[118:121], v[110:113], v[64:79]
	ds_read_b128 v[110:113], v114 offset:49152
	ds_read_b128 v[114:117], v114 offset:57344
	v_mov_b32_e32 v118, v150
	v_mov_b32_e32 v119, v151
	v_mov_b32_e32 v120, v148
	v_mov_b32_e32 v121, v149
	s_waitcnt lgkmcnt(1)
	v_mfma_f32_32x32x16_bf16 v[80:95], v[110:113], v[106:109], v[80:95]
	v_add_u32_e32 v110, s16, v223
	s_waitcnt lgkmcnt(0)
	v_mfma_f32_32x32x16_bf16 v[64:79], v[114:117], v[106:109], v[64:79]
	ds_read_b128 v[106:109], v110 offset:49152
	ds_read_b128 v[110:113], v110 offset:57344
	v_mov_b32_e32 v114, v154
	v_mov_b32_e32 v115, v155
	v_mov_b32_e32 v116, v152
	v_mov_b32_e32 v117, v153
	s_waitcnt lgkmcnt(1)
	v_mfma_f32_32x32x16_bf16 v[80:95], v[106:109], v[102:105], v[80:95]
	v_add_u32_e32 v106, s16, v224
	s_waitcnt lgkmcnt(0)
	v_mfma_f32_32x32x16_bf16 v[64:79], v[110:113], v[102:105], v[64:79]
	ds_read_b128 v[102:105], v106 offset:49152
	ds_read_b128 v[106:109], v106 offset:57344
	v_mov_b32_e32 v110, v158
	v_mov_b32_e32 v111, v159
	v_mov_b32_e32 v112, v156
	v_mov_b32_e32 v113, v157
	s_waitcnt lgkmcnt(1)
	v_mfma_f32_32x32x16_bf16 v[80:95], v[102:105], v[98:101], v[80:95]
	s_waitcnt lgkmcnt(0)
	v_mfma_f32_32x32x16_bf16 v[64:79], v[106:109], v[98:101], v[64:79]
	v_add_f32_e32 v98, 0, v163
	v_add_f32_e32 v98, v177, v98
	v_add_f32_e32 v98, v164, v98
	v_add_f32_e32 v98, v229, v98
	v_add_f32_e32 v98, v176, v98
	v_add_f32_e32 v98, v230, v98
	v_add_f32_e32 v98, v165, v98
	v_add_f32_e32 v98, v175, v98
	v_add_f32_e32 v98, v171, v98
	v_add_f32_e32 v98, v173, v98
	v_add_f32_e32 v98, v172, v98
	v_add_f32_e32 v98, v174, v98
	v_mov_b32_e32 v108, v160
	v_add_f32_e32 v98, v167, v98
	v_mov_b32_e32 v109, v161
	v_add_f32_e32 v98, v169, v98
	v_add_f32_e32 v98, v168, v98
	v_add_f32_e32 v98, v170, v98
	v_add_f32_e32 v98, v108, v98
	v_add_f32_e32 v98, v109, v98
	v_add_f32_e32 v98, v110, v98
	v_add_f32_e32 v98, v111, v98
	v_add_f32_e32 v98, v112, v98
	v_add_f32_e32 v98, v113, v98
	v_add_f32_e32 v98, v114, v98
	v_add_f32_e32 v98, v115, v98
	v_add_f32_e32 v98, v116, v98
	v_add_f32_e32 v98, v117, v98
	v_add_f32_e32 v98, v118, v98
	v_add_f32_e32 v98, v119, v98
	v_add_f32_e32 v98, v120, v98
	v_add_f32_e32 v98, v121, v98
	v_add_f32_e32 v98, v122, v98
	v_add_f32_e32 v102, v123, v98
	v_mov_b32_e32 v103, v102
	v_cvt_pk_bf16_f32 v98, v163, v177
	v_cvt_pk_bf16_f32 v99, v164, v229
	v_cvt_pk_bf16_f32 v100, v176, v230
	v_cvt_pk_bf16_f32 v101, v165, v175
	s_nop 1
	v_permlane32_swap_b32_e32 v102, v103
	v_cvt_pk_bf16_f32 v104, v171, v173
	v_cvt_pk_bf16_f32 v105, v172, v174
	v_cvt_pk_bf16_f32 v106, v167, v169
	v_cvt_pk_bf16_f32 v107, v168, v170
	v_cvt_pk_bf16_f32 v108, v108, v109
	v_cvt_pk_bf16_f32 v109, v110, v111
	v_cvt_pk_bf16_f32 v110, v112, v113
	v_cvt_pk_bf16_f32 v111, v114, v115
	v_cvt_pk_bf16_f32 v112, v116, v117
	v_cvt_pk_bf16_f32 v113, v118, v119
	v_cvt_pk_bf16_f32 v114, v120, v121
	v_cvt_pk_bf16_f32 v115, v122, v123
	s_nop 0
	v_add_u32_e32 v132, s12, v212
	ds_read_b64_tr_b16 v[116:117], v132 offset:0
	ds_read_b64_tr_b16 v[118:119], v132 offset:0x800
	ds_read_b64_tr_b16 v[120:121], v132 offset:0x1000
	ds_read_b64_tr_b16 v[122:123], v132 offset:0x1800
	ds_read_b64_tr_b16 v[124:125], v132 offset:0x2000
	ds_read_b64_tr_b16 v[126:127], v132 offset:0x2800
	ds_read_b64_tr_b16 v[128:129], v132 offset:0x3000
	ds_read_b64_tr_b16 v[130:131], v132 offset:0x3800
	s_waitcnt lgkmcnt(0)
	s_nop 0
	v_mfma_f32_32x32x16_bf16 v[0:15], v[98:101], v[116:119], v[0:15]
	ds_read_b64_tr_b16 v[116:117], v132 offset:0x200
	ds_read_b64_tr_b16 v[118:119], v132 offset:0xa00
	v_mfma_f32_32x32x16_bf16 v[0:15], v[104:107], v[120:123], v[0:15]
	ds_read_b64_tr_b16 v[120:121], v132 offset:0x1200
	ds_read_b64_tr_b16 v[122:123], v132 offset:0x1a00
	v_mfma_f32_32x32x16_bf16 v[0:15], v[108:111], v[124:127], v[0:15]
	ds_read_b64_tr_b16 v[124:125], v132 offset:0x2200
	ds_read_b64_tr_b16 v[126:127], v132 offset:0x2a00
	v_mfma_f32_32x32x16_bf16 v[0:15], v[112:115], v[128:131], v[0:15]
	ds_read_b64_tr_b16 v[128:129], v132 offset:0x3200
	ds_read_b64_tr_b16 v[130:131], v132 offset:0x3a00
	s_waitcnt lgkmcnt(0)
; #define RESC(a) do { if (__any((a) < 1.f)) { if (hi == 0) al_l[r32] = (a); asm volatile("s_waitcnt lgkmcnt(0)" ::: "memory"); \
;     _Pragma("unroll") for (int d = 0; d < 4; ++d) _Pragma("unroll") for (int r = 0; r < 16; ++r) o[d][r] *= al_l[crow(r, hi)]; } } while (0)
; __device__ __forceinline__ void partialSM(f32x16& p0, f32x16& p1, float& m_reg, float& mn, float& alpha) {
;     constexpr float C = SCALE * 1.4426950408889634f;
;     float pmax = p0[0];
; #pragma unroll
;     for (int r = 1; r < 16; ++r) pmax = fmaxf(pmax, p0[r]);
; #pragma unroll
;     for (int r = 0; r < 16; ++r) pmax = fmaxf(pmax, p1[r]);
;     { auto rr = __builtin_amdgcn_permlane32_swap(__float_as_uint(pmax), __float_as_uint(pmax), false, false);
;       pmax = fmaxf(__uint_as_float(rr[0]), __uint_as_float(rr[1])); }
;     if (__builtin_expect(__all(pmax - m_reg <= THR / SCALE), 1)) { mn = m_reg; alpha = 1.f; }
;     else { mn = fmaxf(m_reg, pmax); alpha = __builtin_amdgcn_exp2f((m_reg - mn) * C); m_reg = mn; }
; __device__ __forceinline__ void attn_dense_body(const bf16_t* __restrict__ Qb, const bf16_t* __restrict__ Kh, const bf16_t* __restrict__ Vh,
;                                                 bf16_t* __restrict__ Ob, int seq, char* lds, int dry) {
;     ...
;     pv_d0(o, vb0 + ov, pa0, pa1, pa2, pa3); partialSM(pB0, pB1, m_reg, mnB, alB);
;     RESC(alB);
	v_mfma_f32_32x32x16_bf16 v[48:63], v[98:101], v[116:119], v[48:63]
	ds_read_b64_tr_b16 v[116:117], v132 offset:0x400
	ds_read_b64_tr_b16 v[118:119], v132 offset:0xc00
	v_mfma_f32_32x32x16_bf16 v[48:63], v[104:107], v[120:123], v[48:63]
	ds_read_b64_tr_b16 v[120:121], v132 offset:0x1400
	ds_read_b64_tr_b16 v[122:123], v132 offset:0x1c00
	v_mfma_f32_32x32x16_bf16 v[48:63], v[108:111], v[124:127], v[48:63]
	ds_read_b64_tr_b16 v[124:125], v132 offset:0x2400
	ds_read_b64_tr_b16 v[126:127], v132 offset:0x2c00
	v_mfma_f32_32x32x16_bf16 v[48:63], v[112:115], v[128:131], v[48:63]
	ds_read_b64_tr_b16 v[128:129], v132 offset:0x3400
	ds_read_b64_tr_b16 v[130:131], v132 offset:0x3c00
	s_waitcnt lgkmcnt(0)
	v_mfma_f32_32x32x16_bf16 v[32:47], v[98:101], v[116:119], v[32:47]
	ds_read_b64_tr_b16 v[116:117], v132 offset:0x600
	ds_read_b64_tr_b16 v[118:119], v132 offset:0xe00
	v_mfma_f32_32x32x16_bf16 v[32:47], v[104:107], v[120:123], v[32:47]
	ds_read_b64_tr_b16 v[120:121], v132 offset:0x1600
	ds_read_b64_tr_b16 v[122:123], v132 offset:0x1e00
	v_mfma_f32_32x32x16_bf16 v[32:47], v[108:111], v[124:127], v[32:47]
	ds_read_b64_tr_b16 v[124:125], v132 offset:0x2600
	ds_read_b64_tr_b16 v[126:127], v132 offset:0x2e00
	v_mfma_f32_32x32x16_bf16 v[32:47], v[112:115], v[128:131], v[32:47]
	ds_read_b64_tr_b16 v[128:129], v132 offset:0x3600
	ds_read_b64_tr_b16 v[130:131], v132 offset:0x3e00
	s_waitcnt lgkmcnt(0)
	v_mfma_f32_32x32x16_bf16 v[16:31], v[98:101], v[116:119], v[16:31]
	v_max_f32_e32 v98, v81, v81
	v_max_f32_e32 v99, v80, v80
	v_max_f32_e32 v98, v99, v98
	v_max3_f32 v98, v98, v82, v83
	v_max3_f32 v98, v98, v84, v85
	v_max3_f32 v98, v98, v86, v87
	v_max3_f32 v98, v98, v88, v89
	v_max3_f32 v98, v98, v90, v91
	v_max3_f32 v98, v98, v92, v93
	v_mfma_f32_32x32x16_bf16 v[16:31], v[104:107], v[120:123], v[16:31]
	v_max3_f32 v98, v98, v94, v95
	v_max3_f32 v98, v98, v64, v65
	v_max3_f32 v98, v98, v66, v67
	v_max3_f32 v98, v98, v68, v69
	v_max3_f32 v98, v98, v70, v71
	v_max3_f32 v98, v98, v72, v73
	v_max3_f32 v98, v98, v74, v75
	v_max3_f32 v98, v98, v76, v77
	v_mfma_f32_32x32x16_bf16 v[16:31], v[108:111], v[124:127], v[16:31]
	v_max3_f32 v98, v98, v78, v79
	v_mov_b32_e32 v99, v98
	s_nop 1
	v_permlane32_swap_b32_e32 v98, v99
	v_max_f32_e32 v99, v99, v99
	v_max_f32_e32 v98, v98, v98
	v_max_f32_e32 v98, v98, v99
	v_sub_f32_e32 v99, v98, v166
	v_cmp_ge_f32_e32 vcc, s72, v99
	v_max_f32_e32 v99, v166, v166
	v_max_f32_e32 v99, v99, v98
	v_mfma_f32_32x32x16_bf16 v[16:31], v[112:115], v[128:131], v[16:31]
	v_sub_f32_e32 v98, v166, v99
	v_mul_f32_e32 v98, 0x3e0293ee, v98
	v_exp_f32_e32 v98, v98
	s_cmp_eq_u64 vcc, exec
	s_cselect_b64 s[8:9], -1, 0
	v_cndmask_b32_e64 v98, v98, 1.0, s[8:9]
	v_cmp_gt_f32_e32 vcc, 1.0, v98
	s_cbranch_vccz .LBB0_285
	s_and_saveexec_b64 s[10:11], s[6:7]
	ds_write_b32 v209, v98 offset:128
	s_or_b64 exec, exec, s[10:11]
	s_waitcnt lgkmcnt(0)
	v_add_u32_e32 v100, v179, v96
	ds_read_b128 v[104:107], v100 offset:224
	ds_read_b128 v[108:111], v100 offset:192
	ds_read_b128 v[112:115], v100 offset:160
	ds_read_b128 v[116:119], v100 offset:128
	s_waitcnt lgkmcnt(3)
	v_pk_mul_f32 v[12:13], v[12:13], v[104:105]
	s_waitcnt lgkmcnt(2)
	v_pk_mul_f32 v[8:9], v[8:9], v[108:109]
	s_waitcnt lgkmcnt(1)
	v_pk_mul_f32 v[4:5], v[4:5], v[112:113]
	v_pk_mul_f32 v[14:15], v[14:15], v[106:107]
	v_pk_mul_f32 v[10:11], v[10:11], v[110:111]
	v_pk_mul_f32 v[6:7], v[6:7], v[114:115]
	s_waitcnt lgkmcnt(0)
	v_pk_mul_f32 v[2:3], v[2:3], v[118:119]
	v_pk_mul_f32 v[0:1], v[0:1], v[116:117]
	v_pk_mul_f32 v[60:61], v[60:61], v[104:105]
	v_pk_mul_f32 v[56:57], v[56:57], v[108:109]
	v_pk_mul_f32 v[52:53], v[52:53], v[112:113]
	v_pk_mul_f32 v[62:63], v[62:63], v[106:107]
	v_pk_mul_f32 v[58:59], v[58:59], v[110:111]
	v_pk_mul_f32 v[54:55], v[54:55], v[114:115]
	v_pk_mul_f32 v[50:51], v[50:51], v[118:119]
	v_pk_mul_f32 v[48:49], v[48:49], v[116:117]
	v_pk_mul_f32 v[44:45], v[44:45], v[104:105]
	v_pk_mul_f32 v[40:41], v[40:41], v[108:109]
	v_pk_mul_f32 v[36:37], v[36:37], v[112:113]
	v_pk_mul_f32 v[46:47], v[46:47], v[106:107]
	v_pk_mul_f32 v[42:43], v[42:43], v[110:111]
	v_pk_mul_f32 v[38:39], v[38:39], v[114:115]
	v_pk_mul_f32 v[34:35], v[34:35], v[118:119]
	v_pk_mul_f32 v[32:33], v[32:33], v[116:117]
	v_pk_mul_f32 v[28:29], v[28:29], v[104:105]
	v_pk_mul_f32 v[24:25], v[24:25], v[108:109]
	v_pk_mul_f32 v[20:21], v[20:21], v[112:113]
	v_pk_mul_f32 v[30:31], v[30:31], v[106:107]
	v_pk_mul_f32 v[26:27], v[26:27], v[110:111]
	v_pk_mul_f32 v[22:23], v[22:23], v[114:115]
	v_pk_mul_f32 v[18:19], v[18:19], v[118:119]
	v_pk_mul_f32 v[16:17], v[16:17], v[116:117]
; __device__ __forceinline__ void partialSM(f32x16& p0, f32x16& p1, float& m_reg, float& mn, float& alpha) {
;     ...
;     float mnC = -mn * C;
; #pragma unroll
;     for (int r = 0; r < 16; ++r) p0[r] = fmaf(p0[r], C, mnC);
; #pragma unroll
;     for (int r = 0; r < 16; ++r) p1[r] = fmaf(p1[r], C, mnC);
; #pragma unroll
;     for (int r = 0; r < 16; ++r) p0[r] = __builtin_amdgcn_exp2f(p0[r]);
; }
; __device__ __forceinline__ void finishSM(f32x16& p0, f32x16& p1, float alpha, float& l_reg, bf16x8& pa0, bf16x8& pa1, bf16x8& pa2, bf16x8& pa3) {
; #pragma unroll
;     for (int r = 0; r < 16; ++r) p1[r] = __builtin_amdgcn_exp2f(p1[r]);
;     float ps = 0;
; #pragma unroll
;     for (int r = 0; r < 16; ++r) ps += p0[r];
; #pragma unroll
;     for (int r = 0; r < 16; ++r) ps += p1[r];
;     { auto rr = __builtin_amdgcn_permlane32_swap(__float_as_uint(ps), __float_as_uint(ps), false, false);
;       ps = __uint_as_float(rr[0]) + __uint_as_float(rr[1]); }
;     l_reg = l_reg * alpha + ps;
;     ...
;     PK4(p0, 0, pa0); PK4(p0, 8, pa1); PK4(p1, 0, pa2); PK4(p1, 8, pa3);
;     ...
; }
; __device__ __forceinline__ void qkt(f32x16& p0, f32x16& p1, const bf16_t* Ks, const bf16x8* qr, int r32, int hi) {
;     p0 = f32x16{}; p1 = f32x16{};
; #pragma unroll
;     for (int d0 = 0; d0 < 8; ++d0) { int cb = (d0 * 16 + hi * 8) * 2;
;         bf16x8 b0 = *reinterpret_cast<const bf16x8*>((const char*)Ks + KSWZ(r32, cb));
;         bf16x8 b1 = *reinterpret_cast<const bf16x8*>((const char*)Ks + KSWZ(32 + r32, cb));
;         p0 = __builtin_amdgcn_mfma_f32_32x32x16_bf16(b0, qr[d0], p0, 0, 0, 0);
;         p1 = __builtin_amdgcn_mfma_f32_32x32x16_bf16(b1, qr[d0], p1, 0, 0, 0); }
; }
; __device__ __forceinline__ int v_st(int k, int c) { const int kk = (k & ~0xC) | ((k & 4) << 1) | ((k & 8) >> 1); return ((kk >> 3) * 4 + (c >> 5)) * 512 + ((kk & 7) * 32 + (c & 31)) * 2; }
; __device__ __forceinline__ int v_rd_base(int lane) { return ((lane & 3) << 3) | (((lane >> 2) & 3) << 6) | (((lane >> 4) & 1) << 5) | (((lane >> 5) & 1) << 8); }
; template <int OFF> __device__ __forceinline__ s16x4 tr_read(int vb) {
;     s16x4 r; asm volatile("ds_read_b64_tr_b16 %0, %1 offset:%2" : "=&v"(r) : "v"(vb), "i"(OFF) : "memory"); return r;
; }
; template <int D0> __device__ __forceinline__ void pv_one(f32x16& od, int vb, bf16x8 pa0, bf16x8 pa1, bf16x8 pa2, bf16x8 pa3) {
.LBB0_285:
	v_cndmask_b32_e64 v99, v99, v166, s[8:9]
	v_mul_f32_e32 v99, 0xbe0293ee, v99
	v_fmamk_f32 v80, v80, 0x3e0293ee, v99
	v_fmamk_f32 v81, v81, 0x3e0293ee, v99
	v_fmamk_f32 v82, v82, 0x3e0293ee, v99
	v_fmamk_f32 v83, v83, 0x3e0293ee, v99
	v_fmamk_f32 v84, v84, 0x3e0293ee, v99
	v_fmamk_f32 v85, v85, 0x3e0293ee, v99
	v_fmamk_f32 v86, v86, 0x3e0293ee, v99
	v_fmamk_f32 v87, v87, 0x3e0293ee, v99
	v_fmamk_f32 v88, v88, 0x3e0293ee, v99
	v_fmamk_f32 v89, v89, 0x3e0293ee, v99
	v_fmamk_f32 v90, v90, 0x3e0293ee, v99
	v_fmamk_f32 v91, v91, 0x3e0293ee, v99
	v_fmamk_f32 v92, v92, 0x3e0293ee, v99
	v_fmamk_f32 v93, v93, 0x3e0293ee, v99
	v_fmamk_f32 v94, v94, 0x3e0293ee, v99
	v_fmamk_f32 v95, v95, 0x3e0293ee, v99
	v_fmamk_f32 v64, v64, 0x3e0293ee, v99
	v_fmamk_f32 v65, v65, 0x3e0293ee, v99
	v_fmamk_f32 v66, v66, 0x3e0293ee, v99
	v_fmamk_f32 v67, v67, 0x3e0293ee, v99
	v_fmamk_f32 v68, v68, 0x3e0293ee, v99
	v_fmamk_f32 v69, v69, 0x3e0293ee, v99
	v_fmamk_f32 v70, v70, 0x3e0293ee, v99
	v_fmamk_f32 v71, v71, 0x3e0293ee, v99
	v_fmamk_f32 v72, v72, 0x3e0293ee, v99
	v_fmamk_f32 v73, v73, 0x3e0293ee, v99
	v_fmamk_f32 v74, v74, 0x3e0293ee, v99
	v_fmamk_f32 v75, v75, 0x3e0293ee, v99
	v_fmamk_f32 v76, v76, 0x3e0293ee, v99
	v_fmamk_f32 v77, v77, 0x3e0293ee, v99
	v_fmamk_f32 v78, v78, 0x3e0293ee, v99
	v_fmac_f32_e32 v99, 0x3e0293ee, v79
	v_exp_f32_e32 v79, v80
	v_exp_f32_e32 v80, v81
	v_exp_f32_e32 v81, v82
	v_exp_f32_e32 v82, v83
	v_exp_f32_e32 v83, v84
	v_exp_f32_e32 v84, v85
	v_exp_f32_e32 v85, v86
	v_exp_f32_e32 v86, v87
	v_exp_f32_e32 v87, v88
	v_exp_f32_e32 v88, v89
	v_exp_f32_e32 v89, v90
	v_exp_f32_e32 v90, v91
	v_exp_f32_e32 v91, v92
	v_exp_f32_e32 v92, v93
	v_exp_f32_e32 v93, v94
	v_exp_f32_e32 v94, v95
	v_exp_f32_e32 v95, v64
	v_add_f32_e32 v64, 0, v79
	v_add_f32_e32 v64, v80, v64
	v_add_f32_e32 v64, v81, v64
	v_add_f32_e32 v64, v82, v64
	v_add_f32_e32 v64, v83, v64
	v_add_f32_e32 v64, v84, v64
	v_add_f32_e32 v64, v85, v64
	v_add_f32_e32 v64, v86, v64
	v_add_f32_e32 v64, v87, v64
	v_add_f32_e32 v64, v88, v64
	v_add_f32_e32 v64, v89, v64
	v_add_f32_e32 v64, v90, v64
	v_add_f32_e32 v64, v91, v64
	v_exp_f32_e32 v100, v65
	v_add_f32_e32 v64, v92, v64
	v_exp_f32_e32 v101, v66
	v_add_f32_e32 v64, v93, v64
	v_exp_f32_e32 v104, v67
	v_add_f32_e32 v64, v94, v64
	v_exp_f32_e32 v105, v68
	v_add_f32_e32 v64, v95, v64
	v_exp_f32_e32 v106, v69
	v_add_f32_e32 v64, v100, v64
	v_exp_f32_e32 v107, v70
	v_add_f32_e32 v64, v101, v64
	v_exp_f32_e32 v108, v71
	v_add_f32_e32 v64, v104, v64
	v_exp_f32_e32 v109, v72
	v_add_f32_e32 v64, v105, v64
	v_exp_f32_e32 v110, v73
	v_add_f32_e32 v64, v106, v64
	v_exp_f32_e32 v111, v74
	v_add_f32_e32 v64, v107, v64
	v_exp_f32_e32 v112, v75
	v_add_f32_e32 v64, v108, v64
	v_exp_f32_e32 v113, v76
	v_add_f32_e32 v64, v109, v64
	v_exp_f32_e32 v114, v77
	v_add_f32_e32 v64, v110, v64
	v_exp_f32_e32 v115, v78
	v_add_f32_e32 v64, v111, v64
	v_exp_f32_e32 v99, v99
	v_add_f32_e32 v64, v112, v64
	v_add_f32_e32 v64, v113, v64
	v_add_f32_e32 v64, v114, v64
	v_add_f32_e32 v64, v115, v64
	v_add_f32_e32 v64, v99, v64
	v_mov_b32_e32 v65, v64
	s_nop 1
	v_permlane32_swap_b32_e32 v64, v65
	v_cvt_pk_bf16_f32 v66, v79, v80
	v_cvt_pk_bf16_f32 v67, v81, v82
	v_cvt_pk_bf16_f32 v68, v83, v84
	v_cvt_pk_bf16_f32 v69, v85, v86
	v_cvt_pk_bf16_f32 v70, v87, v88
	v_cvt_pk_bf16_f32 v71, v89, v90
	v_cvt_pk_bf16_f32 v72, v91, v92
	v_cvt_pk_bf16_f32 v73, v93, v94
	v_cvt_pk_bf16_f32 v74, v95, v100
	v_cvt_pk_bf16_f32 v75, v101, v104
	v_cvt_pk_bf16_f32 v76, v105, v106
	v_cvt_pk_bf16_f32 v77, v107, v108
	v_cvt_pk_bf16_f32 v78, v109, v110
	v_cvt_pk_bf16_f32 v79, v111, v112
	v_cvt_pk_bf16_f32 v80, v113, v114
	v_cvt_pk_bf16_f32 v81, v115, v99
	s_nop 0
	ds_read_b64_tr_b16 v[82:83], v211 offset:0
	ds_read_b64_tr_b16 v[84:85], v211 offset:0x800
	ds_read_b64_tr_b16 v[86:87], v211 offset:0x1000
	ds_read_b64_tr_b16 v[88:89], v211 offset:0x1800
	ds_read_b64_tr_b16 v[90:91], v211 offset:0x2000
	ds_read_b64_tr_b16 v[92:93], v211 offset:0x2800
	ds_read_b64_tr_b16 v[104:105], v211 offset:0x3000
	ds_read_b64_tr_b16 v[106:107], v211 offset:0x3800
	s_waitcnt lgkmcnt(0)
	s_nop 0
	v_mfma_f32_32x32x16_bf16 v[0:15], v[66:69], v[82:85], v[0:15]
	ds_read_b64_tr_b16 v[82:83], v211 offset:0x200
	ds_read_b64_tr_b16 v[84:85], v211 offset:0xa00
	v_mfma_f32_32x32x16_bf16 v[0:15], v[70:73], v[86:89], v[0:15]
	ds_read_b64_tr_b16 v[86:87], v211 offset:0x1200
	ds_read_b64_tr_b16 v[88:89], v211 offset:0x1a00
	v_mfma_f32_32x32x16_bf16 v[0:15], v[74:77], v[90:93], v[0:15]
	ds_read_b64_tr_b16 v[90:91], v211 offset:0x2200
	ds_read_b64_tr_b16 v[92:93], v211 offset:0x2a00
	v_mfma_f32_32x32x16_bf16 v[0:15], v[78:81], v[104:107], v[0:15]
	ds_read_b64_tr_b16 v[104:105], v211 offset:0x3200
	ds_read_b64_tr_b16 v[106:107], v211 offset:0x3a00
	s_waitcnt lgkmcnt(0)
	v_mfma_f32_32x32x16_bf16 v[48:63], v[66:69], v[82:85], v[48:63]
	ds_read_b64_tr_b16 v[82:83], v211 offset:0x400
	ds_read_b64_tr_b16 v[84:85], v211 offset:0xc00
	v_mfma_f32_32x32x16_bf16 v[48:63], v[70:73], v[86:89], v[48:63]
	ds_read_b64_tr_b16 v[86:87], v211 offset:0x1400
	ds_read_b64_tr_b16 v[88:89], v211 offset:0x1c00
	v_mfma_f32_32x32x16_bf16 v[48:63], v[74:77], v[90:93], v[48:63]
	ds_read_b64_tr_b16 v[90:91], v211 offset:0x2400
	ds_read_b64_tr_b16 v[92:93], v211 offset:0x2c00
	v_mfma_f32_32x32x16_bf16 v[48:63], v[78:81], v[104:107], v[48:63]
	ds_read_b64_tr_b16 v[104:105], v211 offset:0x3400
	ds_read_b64_tr_b16 v[106:107], v211 offset:0x3c00
	s_waitcnt lgkmcnt(0)
	v_mfma_f32_32x32x16_bf16 v[32:47], v[66:69], v[82:85], v[32:47]
	ds_read_b64_tr_b16 v[82:83], v211 offset:0x600
	ds_read_b64_tr_b16 v[84:85], v211 offset:0xe00
	v_mfma_f32_32x32x16_bf16 v[32:47], v[70:73], v[86:89], v[32:47]
	ds_read_b64_tr_b16 v[86:87], v211 offset:0x1600
	ds_read_b64_tr_b16 v[88:89], v211 offset:0x1e00
	v_mfma_f32_32x32x16_bf16 v[32:47], v[74:77], v[90:93], v[32:47]
	ds_read_b64_tr_b16 v[90:91], v211 offset:0x2600
	ds_read_b64_tr_b16 v[92:93], v211 offset:0x2e00
	v_mfma_f32_32x32x16_bf16 v[32:47], v[78:81], v[104:107], v[32:47]
	ds_read_b64_tr_b16 v[104:105], v211 offset:0x3600
	ds_read_b64_tr_b16 v[106:107], v211 offset:0x3e00
	s_waitcnt lgkmcnt(0)
	v_mfma_f32_32x32x16_bf16 v[16:31], v[66:69], v[82:85], v[16:31]
	v_mfma_f32_32x32x16_bf16 v[16:31], v[70:73], v[86:89], v[16:31]
	v_mfma_f32_32x32x16_bf16 v[16:31], v[74:77], v[90:93], v[16:31]
	v_mfma_f32_32x32x16_bf16 v[16:31], v[78:81], v[104:107], v[16:31]
	s_and_saveexec_b64 s[8:9], s[6:7]
	v_add_f32_e32 v66, v102, v103
	v_fmac_f32_e32 v66, v210, v162
	v_add_f32_e32 v64, v64, v65
	v_fmac_f32_e32 v64, v66, v98
	ds_write_b32 v209, v64
	s_or_b64 exec, exec, s[8:9]
	s_waitcnt lgkmcnt(0)
	s_andn2_b64 vcc, exec, s[0:1]
	s_cbranch_vccnz .LBB0_267
; __device__ __forceinline__ unsigned cvt_pk_bf16(float lo, float hi) { unsigned r; asm volatile("v_cvt_pk_bf16_f32 %0, %1, %2" : "=v"(r) : "v"(lo), "v"(hi)); return r; }
; __device__ __forceinline__ int crow(int r, int hi) { return (r & 3) + 8 * (r >> 2) + 4 * hi; }
; __device__ __forceinline__ void attn_dense_body(const bf16_t* __restrict__ Qb, const bf16_t* __restrict__ Kh, const bf16_t* __restrict__ Vh,
;                                                 bf16_t* __restrict__ Ob, int seq, char* lds, int dry) {
;     ...
;     if (hi == 0) li_l[r32] = l_reg; asm volatile("s_waitcnt lgkmcnt(0)" ::: "memory");
;     float rli[16];
; #pragma unroll
;     for (int r = 0; r < 16; ++r) rli[r] = __builtin_amdgcn_rcpf(li_l[crow(r, hi)]);
;     bf16_t* Ow = Ob + (long)(wid * QBLK) * LDO;
;     if (!dry)
; #pragma unroll
;     for (int r = 0; r < 16; ++r) { int orow = crow(r, hi);
; #pragma unroll
;         for (int d0 = 0; d0 < 4; ++d0) Ow[(long)orow * LDO + d0 * 32 + r32] = (bf16_t)(cvt_pk_bf16(o[d0][r] * rli[r], 0.f) & 0xffffu); }
	v_add_u32_e32 v68, v179, v96
	ds_read_b128 v[64:67], v68 offset:96
	s_lshl_b64 s[4:5], s[4:5], 11
	s_add_u32 s4, s33, s4
	s_addc_u32 s5, s34, s5
	s_lshl_b32 s6, s35, 1
	s_waitcnt lgkmcnt(0)
	v_rcp_f32_e32 v72, v67
	v_rcp_f32_e32 v73, v66
	v_rcp_f32_e32 v74, v65
	v_rcp_f32_e32 v75, v64
	ds_read_b128 v[64:67], v68 offset:64
	s_add_u32 s4, s4, s6
	v_ashrrev_i32_e32 v179, 31, v178
	s_addc_u32 s5, s5, 0
	v_lshlrev_b32_e32 v96, 1, v208
	s_waitcnt lgkmcnt(0)
	v_rcp_f32_e32 v76, v67
	v_rcp_f32_e32 v77, v66
	v_rcp_f32_e32 v78, v65
	v_rcp_f32_e32 v79, v64
	ds_read_b128 v[64:67], v68
	ds_read_b128 v[68:71], v68 offset:32
	s_waitcnt lgkmcnt(1)
	v_rcp_f32_e32 v83, v64
	v_rcp_f32_e32 v82, v65
	v_lshlrev_b64 v[64:65], 11, v[178:179]
	v_lshl_add_u64 v[64:65], s[4:5], 0, v[64:65]
	v_rcp_f32_e32 v80, v67
	v_rcp_f32_e32 v81, v66
	v_lshlrev_b32_e32 v66, 13, v207
	v_lshl_add_u64 v[64:65], v[64:65], 0, v[96:97]
	v_mov_b32_e32 v67, v97
	v_mul_f32_e32 v0, v0, v83
	v_lshl_add_u64 v[64:65], v[64:65], 0, v[66:67]
	v_cvt_pk_bf16_f32 v0, v0, v97
	global_store_short v[64:65], v0, off
	v_mul_f32_e32 v0, v48, v83
	v_cvt_pk_bf16_f32 v0, v0, v97
	global_store_short v[64:65], v0, off offset:64
	v_mul_f32_e32 v0, v32, v83
	v_cvt_pk_bf16_f32 v0, v0, v97
	global_store_short v[64:65], v0, off offset:128
	v_mul_f32_e32 v0, v16, v83
	v_cvt_pk_bf16_f32 v0, v0, v97
	global_store_short v[64:65], v0, off offset:192
	v_mul_f32_e32 v0, v1, v82
	v_cvt_pk_bf16_f32 v0, v0, v97
	global_store_short v[64:65], v0, off offset:2048
	v_mul_f32_e32 v0, v49, v82
	v_cvt_pk_bf16_f32 v0, v0, v97
	global_store_short v[64:65], v0, off offset:2112
	v_mul_f32_e32 v0, v33, v82
	v_cvt_pk_bf16_f32 v0, v0, v97
	global_store_short v[64:65], v0, off offset:2176
	v_mul_f32_e32 v0, v17, v82
	v_cvt_pk_bf16_f32 v0, v0, v97
	global_store_short v[64:65], v0, off offset:2240
	v_mul_f32_e32 v0, v2, v81
	v_cvt_pk_bf16_f32 v2, v0, v97
	v_add_co_u32_e32 v0, vcc, s74, v64
	s_waitcnt lgkmcnt(0)
; __device__ __forceinline__ unsigned cvt_pk_bf16(float lo, float hi) { unsigned r; asm volatile("v_cvt_pk_bf16_f32 %0, %1, %2" : "=v"(r) : "v"(lo), "v"(hi)); return r; }
; __device__ __forceinline__ int crow(int r, int hi) { return (r & 3) + 8 * (r >> 2) + 4 * hi; }
; __device__ __forceinline__ void attn_dense_body(const bf16_t* __restrict__ Qb, const bf16_t* __restrict__ Kh, const bf16_t* __restrict__ Vh,
;                                                 bf16_t* __restrict__ Ob, int seq, char* lds, int dry) {
;     ...
;     for (int r = 0; r < 16; ++r) rli[r] = __builtin_amdgcn_rcpf(li_l[crow(r, hi)]);
;     bf16_t* Ow = Ob + (long)(wid * QBLK) * LDO;
;     if (!dry)
; #pragma unroll
;     for (int r = 0; r < 16; ++r) { int orow = crow(r, hi);
; #pragma unroll
;         for (int d0 = 0; d0 < 4; ++d0) Ow[(long)orow * LDO + d0 * 32 + r32] = (bf16_t)(cvt_pk_bf16(o[d0][r] * rli[r], 0.f) & 0xffffu); }
	v_rcp_f32_e32 v68, v68
	v_addc_co_u32_e32 v1, vcc, 0, v65, vcc
	global_store_short v[0:1], v2, off
	v_mul_f32_e32 v2, v50, v81
	v_cvt_pk_bf16_f32 v2, v2, v97
	global_store_short v[0:1], v2, off offset:64
	v_mul_f32_e32 v2, v34, v81
	v_cvt_pk_bf16_f32 v2, v2, v97
	global_store_short v[0:1], v2, off offset:128
	v_mul_f32_e32 v2, v18, v81
	v_cvt_pk_bf16_f32 v2, v2, v97
	global_store_short v[0:1], v2, off offset:192
	v_mul_f32_e32 v2, v3, v80
	v_cvt_pk_bf16_f32 v2, v2, v97
	global_store_short v[0:1], v2, off offset:2048
	v_mul_f32_e32 v2, v51, v80
	v_cvt_pk_bf16_f32 v2, v2, v97
	global_store_short v[0:1], v2, off offset:2112
	v_mul_f32_e32 v2, v35, v80
	v_cvt_pk_bf16_f32 v2, v2, v97
	global_store_short v[0:1], v2, off offset:2176
	v_mul_f32_e32 v2, v19, v80
	v_cvt_pk_bf16_f32 v2, v2, v97
	global_store_short v[0:1], v2, off offset:2240
	v_mul_f32_e32 v0, v4, v68
	s_movk_i32 s4, 0x4000
	v_cvt_pk_bf16_f32 v4, v0, v97
	v_add_co_u32_e32 v0, vcc, s4, v64
	s_movk_i32 s4, 0x5000
	s_nop 0
	v_addc_co_u32_e32 v1, vcc, 0, v65, vcc
	v_add_co_u32_e32 v2, vcc, s4, v64
	v_rcp_f32_e32 v69, v69
	s_nop 0
	v_addc_co_u32_e32 v3, vcc, 0, v65, vcc
	global_store_short v[2:3], v4, off offset:-4096
	v_mul_f32_e32 v4, v52, v68
	v_cvt_pk_bf16_f32 v4, v4, v97
	global_store_short v[0:1], v4, off offset:64
	v_mul_f32_e32 v4, v36, v68
	v_cvt_pk_bf16_f32 v4, v4, v97
	global_store_short v[0:1], v4, off offset:128
	v_mul_f32_e32 v4, v20, v68
	v_cvt_pk_bf16_f32 v4, v4, v97
	global_store_short v[0:1], v4, off offset:192
	v_mul_f32_e32 v4, v5, v69
	v_cvt_pk_bf16_f32 v4, v4, v97
	global_store_short v[0:1], v4, off offset:2048
	v_mul_f32_e32 v4, v53, v69
	v_rcp_f32_e32 v70, v70
	v_cvt_pk_bf16_f32 v4, v4, v97
	global_store_short v[0:1], v4, off offset:2112
	v_mul_f32_e32 v4, v37, v69
	v_cvt_pk_bf16_f32 v4, v4, v97
	global_store_short v[0:1], v4, off offset:2176
	v_mul_f32_e32 v4, v21, v69
	v_cvt_pk_bf16_f32 v4, v4, v97
	global_store_short v[0:1], v4, off offset:2240
	v_mul_f32_e32 v0, v6, v70
	v_cvt_pk_bf16_f32 v0, v0, v97
	global_store_short v[2:3], v0, off
	v_mul_f32_e32 v0, v54, v70
	v_cvt_pk_bf16_f32 v0, v0, v97
	v_rcp_f32_e32 v71, v71
	global_store_short v[2:3], v0, off offset:64
	v_mul_f32_e32 v0, v38, v70
	v_cvt_pk_bf16_f32 v0, v0, v97
	global_store_short v[2:3], v0, off offset:128
	v_mul_f32_e32 v0, v22, v70
	v_cvt_pk_bf16_f32 v0, v0, v97
	global_store_short v[2:3], v0, off offset:192
	v_mul_f32_e32 v0, v7, v71
	v_cvt_pk_bf16_f32 v0, v0, v97
	global_store_short v[2:3], v0, off offset:2048
	v_mul_f32_e32 v0, v55, v71
	v_cvt_pk_bf16_f32 v0, v0, v97
	global_store_short v[2:3], v0, off offset:2112
	v_mul_f32_e32 v0, v39, v71
	v_cvt_pk_bf16_f32 v0, v0, v97
	global_store_short v[2:3], v0, off offset:2176
	v_mul_f32_e32 v0, v23, v71
	v_cvt_pk_bf16_f32 v0, v0, v97
	global_store_short v[2:3], v0, off offset:2240
	v_mul_f32_e32 v0, v8, v79
	s_mov_b32 s4, 0x8000
	v_cvt_pk_bf16_f32 v4, v0, v97
	v_add_co_u32_e32 v0, vcc, s4, v64
	s_mov_b32 s4, 0xd000
	s_nop 0
	v_addc_co_u32_e32 v1, vcc, 0, v65, vcc
	v_add_co_u32_e32 v2, vcc, s75, v64
	s_nop 1
	v_addc_co_u32_e32 v3, vcc, 0, v65, vcc
	global_store_short v[2:3], v4, off offset:-4096
	v_mul_f32_e32 v4, v56, v79
	v_cvt_pk_bf16_f32 v4, v4, v97
	global_store_short v[0:1], v4, off offset:64
	v_mul_f32_e32 v4, v40, v79
	v_cvt_pk_bf16_f32 v4, v4, v97
	global_store_short v[0:1], v4, off offset:128
	v_mul_f32_e32 v4, v24, v79
	v_cvt_pk_bf16_f32 v4, v4, v97
	global_store_short v[0:1], v4, off offset:192
	v_mul_f32_e32 v4, v9, v78
	v_cvt_pk_bf16_f32 v4, v4, v97
	global_store_short v[0:1], v4, off offset:2048
	v_mul_f32_e32 v4, v57, v78
	v_cvt_pk_bf16_f32 v4, v4, v97
	global_store_short v[0:1], v4, off offset:2112
	v_mul_f32_e32 v4, v41, v78
	v_cvt_pk_bf16_f32 v4, v4, v97
	global_store_short v[0:1], v4, off offset:2176
	v_mul_f32_e32 v4, v25, v78
	v_cvt_pk_bf16_f32 v4, v4, v97
	global_store_short v[0:1], v4, off offset:2240
	v_mul_f32_e32 v0, v10, v77
	v_cvt_pk_bf16_f32 v0, v0, v97
	global_store_short v[2:3], v0, off
	v_mul_f32_e32 v0, v58, v77
	v_cvt_pk_bf16_f32 v0, v0, v97
	global_store_short v[2:3], v0, off offset:64
	v_mul_f32_e32 v0, v42, v77
	v_cvt_pk_bf16_f32 v0, v0, v97
	global_store_short v[2:3], v0, off offset:128
	v_mul_f32_e32 v0, v26, v77
	v_cvt_pk_bf16_f32 v0, v0, v97
	global_store_short v[2:3], v0, off offset:192
	v_mul_f32_e32 v0, v11, v76
	v_cvt_pk_bf16_f32 v0, v0, v97
	global_store_short v[2:3], v0, off offset:2048
	v_mul_f32_e32 v0, v59, v76
	v_cvt_pk_bf16_f32 v0, v0, v97
	global_store_short v[2:3], v0, off offset:2112
	v_mul_f32_e32 v0, v43, v76
	v_cvt_pk_bf16_f32 v0, v0, v97
	global_store_short v[2:3], v0, off offset:2176
	v_mul_f32_e32 v0, v27, v76
	v_cvt_pk_bf16_f32 v0, v0, v97
	global_store_short v[2:3], v0, off offset:2240
	v_mul_f32_e32 v0, v12, v75
	v_cvt_pk_bf16_f32 v4, v0, v97
	v_add_co_u32_e32 v0, vcc, s66, v64
	s_nop 1
	v_addc_co_u32_e32 v1, vcc, 0, v65, vcc
	v_add_co_u32_e32 v2, vcc, s4, v64
	s_nop 1
	v_addc_co_u32_e32 v3, vcc, 0, v65, vcc
	global_store_short v[2:3], v4, off offset:-4096
	v_mul_f32_e32 v4, v60, v75
	v_cvt_pk_bf16_f32 v4, v4, v97
	global_store_short v[0:1], v4, off offset:64
	v_mul_f32_e32 v4, v44, v75
	v_cvt_pk_bf16_f32 v4, v4, v97
	global_store_short v[0:1], v4, off offset:128
	v_mul_f32_e32 v4, v28, v75
	v_cvt_pk_bf16_f32 v4, v4, v97
	global_store_short v[0:1], v4, off offset:192
	v_mul_f32_e32 v4, v13, v74
	v_cvt_pk_bf16_f32 v4, v4, v97
	global_store_short v[0:1], v4, off offset:2048
	v_mul_f32_e32 v4, v61, v74
	v_cvt_pk_bf16_f32 v4, v4, v97
	global_store_short v[0:1], v4, off offset:2112
	v_mul_f32_e32 v4, v45, v74
	v_cvt_pk_bf16_f32 v4, v4, v97
	global_store_short v[0:1], v4, off offset:2176
	v_mul_f32_e32 v4, v29, v74
	v_cvt_pk_bf16_f32 v4, v4, v97
	global_store_short v[0:1], v4, off offset:2240
	v_mul_f32_e32 v0, v14, v73
	v_cvt_pk_bf16_f32 v0, v0, v97
	global_store_short v[2:3], v0, off
	v_mul_f32_e32 v0, v62, v73
	v_cvt_pk_bf16_f32 v0, v0, v97
	global_store_short v[2:3], v0, off offset:64
	v_mul_f32_e32 v0, v46, v73
	v_cvt_pk_bf16_f32 v0, v0, v97
	global_store_short v[2:3], v0, off offset:128
	v_mul_f32_e32 v0, v30, v73
	v_cvt_pk_bf16_f32 v0, v0, v97
	global_store_short v[2:3], v0, off offset:192
	v_mul_f32_e32 v0, v15, v72
	v_cvt_pk_bf16_f32 v0, v0, v97
	global_store_short v[2:3], v0, off offset:2048
	v_mul_f32_e32 v0, v63, v72
	v_cvt_pk_bf16_f32 v0, v0, v97
	global_store_short v[2:3], v0, off offset:2112
	v_mul_f32_e32 v0, v47, v72
	v_cvt_pk_bf16_f32 v0, v0, v97
	global_store_short v[2:3], v0, off offset:2176
	v_mul_f32_e32 v0, v31, v72
	v_cvt_pk_bf16_f32 v0, v0, v97
	global_store_short v[2:3], v0, off offset:2240
	s_branch .LBB0_267
